# v004 plus: deleted the duplicate post-barrier lgkmcnt(0) (already guaranteed by the pre-barrier wait) in the five GEMM K-loops
# baseline (speedup 1.0000x reference)
; #define PG8_STAGE(bufoff, gbase, voff) do { _Pragma("unroll") for (int _i = 0; _i < 2; ++_i) \
;         __builtin_amdgcn_global_load_lds((const unsigned*)((const char*)(gbase) + (voff)[_i]), (PG8_LAS unsigned*)(lds + (bufoff) + ldsw + _i * 8192), 16, 0, 0); } while (0)
; #define PG8_LDA(dst, b, h) do { _Pragma("unroll") for (int m = 0; m < 4; ++m) _Pragma("unroll") for (int k = 0; k < 2; ++k) dst[m][k] = *(const PG8_LAS bf16x8*)(lds + PG8_SA(b, h) + aoff + m * 2048 + k * 1024); } while (0)
; #define PG8_LDB(dst, b, h) do { _Pragma("unroll") for (int n = 0; n < 2; ++n) _Pragma("unroll") for (int k = 0; k < 2; ++k) dst[n][k] = *(const PG8_LAS bf16x8*)(lds + PG8_SB(b, h) + boff + n * 2048 + k * 1024); } while (0)
; #define PG8_MMA(ai, bj, At, Bt) do { __builtin_amdgcn_s_setprio(1); _Pragma("unroll") for (int m = 0; m < 4; ++m) _Pragma("unroll") for (int n = 0; n < 2; ++n) _Pragma("unroll") for (int k = 0; k < 2; ++k) \
;         acc[ai][bj][m][n] = __builtin_amdgcn_mfma_f32_16x16x32_bf16(Bt[n][k], At[m][k], acc[ai][bj][m][n], 0, 0, 0); __builtin_amdgcn_s_setprio(0); } while (0)
; #define PG8_WAIT_V(n) asm volatile("s_waitcnt vmcnt(" #n ")" ::: "memory")
; #define PG8_WAIT_L(n) asm volatile("s_waitcnt lgkmcnt(" #n ")" ::: "memory")
; #define PG8_BAR __builtin_amdgcn_s_barrier()
; #define PG8_SCHED __builtin_amdgcn_sched_barrier(0)
; template <class Epi, class Sched, bool ALIGN_EPI = false, bool SP2 = false>
; __device__ __forceinline__ void gemm_phase(PG8_LAS unsigned char* lds, const Gemm g, const Sched& S, const Epi& E) {
;     ...
;             PG8_LDB(B0, 0, 0); PG8_LDB(B1, 0, 1); PG8_SCHED; PG8_LDA(At, 0, 0); PG8_STAGE(PG8_SA(1, 1), a1 + hstep, voffA);
;             PG8_WAIT_V(8); PG8_WAIT_L(0); PG8_BAR; PG8_MMA(0, 0, At, B0); PG8_MMA(0, 1, At, B1); PG8_BAR; PG8_SCHED;
;             PG8_LDA(At, 0, 1); PG8_STAGE(PG8_SB(0, 0), b2, voffB); PG8_STAGE(PG8_SB(0, 1), b2 + hstep, voffB); PG8_STAGE(PG8_SA(0, 0), a2, voffA);
;             PG8_WAIT_V(8); PG8_WAIT_L(0); PG8_BAR; PG8_MMA(1, 0, At, B0); PG8_MMA(1, 1, At, B1); PG8_BAR; PG8_SCHED;
.LBB0_166:
	s_add_u32 s23, s70, 0xfffc0080
	s_addc_u32 s72, s71, -1
	s_add_i32 s78, 0, 0x10000
	s_cmp_eq_u32 s22, 12
	s_cselect_b32 s75, s57, s72
	s_cselect_b32 s74, s65, s23
	v_add_u32_e32 v138, s78, v166
	s_cselect_b32 s73, s13, s59
	s_cselect_b32 s72, s77, s58
	s_add_i32 s23, 0, 0x14000
	ds_read_b128 v[140:143], v138
	ds_read_b128 v[144:147], v138 offset:1024
	ds_read_b128 v[148:151], v138 offset:2048
	ds_read_b128 v[152:155], v138 offset:3072
	v_add_u32_e32 v138, s23, v166
	ds_read_b128 v[156:159], v138
	ds_read_b128 v[162:165], v138 offset:1024
	ds_read_b128 v[170:173], v138 offset:2048
	ds_read_b128 v[174:177], v138 offset:3072
	v_lshl_add_u64 v[210:211], s[70:71], 0, v[134:135]
	s_add_i32 m0, s3, 0xc000
	ds_read_b128 v[178:181], v168
	ds_read_b128 v[182:185], v168 offset:1024
	ds_read_b128 v[186:189], v168 offset:2048
	ds_read_b128 v[190:193], v168 offset:3072
	ds_read_b128 v[194:197], v168 offset:4096
	ds_read_b128 v[198:201], v168 offset:5120
	ds_read_b128 v[202:205], v168 offset:6144
	ds_read_b128 v[206:209], v168 offset:7168
	global_load_lds_dwordx4 v[210:211], off
	v_lshl_add_u64 v[210:211], s[70:71], 0, v[136:137]
	s_add_i32 m0, s3, 0xe000
	s_nop 0
	global_load_lds_dwordx4 v[210:211], off
	s_waitcnt vmcnt(8)
	s_waitcnt lgkmcnt(0)
	s_barrier
	s_setprio 1
	v_mfma_f32_16x16x32_bf16 v[124:127], v[140:143], v[178:181], v[124:127]
	v_mfma_f32_16x16x32_bf16 v[120:123], v[148:151], v[178:181], v[120:123]
	v_mfma_f32_16x16x32_bf16 v[108:111], v[140:143], v[186:189], v[108:111]
	v_mfma_f32_16x16x32_bf16 v[104:107], v[148:151], v[186:189], v[104:107]
	v_mfma_f32_16x16x32_bf16 v[92:95], v[140:143], v[194:197], v[92:95]
	v_mfma_f32_16x16x32_bf16 v[88:91], v[148:151], v[194:197], v[88:91]
	v_mfma_f32_16x16x32_bf16 v[76:79], v[140:143], v[202:205], v[76:79]
	v_mfma_f32_16x16x32_bf16 v[72:75], v[148:151], v[202:205], v[72:75]
	v_mfma_f32_16x16x32_bf16 v[124:127], v[144:147], v[182:185], v[124:127]
	v_mfma_f32_16x16x32_bf16 v[120:123], v[152:155], v[182:185], v[120:123]
	v_mfma_f32_16x16x32_bf16 v[108:111], v[144:147], v[190:193], v[108:111]
	v_mfma_f32_16x16x32_bf16 v[104:107], v[152:155], v[190:193], v[104:107]
	v_mfma_f32_16x16x32_bf16 v[92:95], v[144:147], v[198:201], v[92:95]
	v_mfma_f32_16x16x32_bf16 v[88:91], v[152:155], v[198:201], v[88:91]
	v_mfma_f32_16x16x32_bf16 v[76:79], v[144:147], v[206:209], v[76:79]
	v_mfma_f32_16x16x32_bf16 v[72:75], v[152:155], v[206:209], v[72:75]
	s_setprio 0
	s_setprio 1
	v_mfma_f32_16x16x32_bf16 v[116:119], v[156:159], v[178:181], v[116:119]
	v_mfma_f32_16x16x32_bf16 v[112:115], v[170:173], v[178:181], v[112:115]
	v_mfma_f32_16x16x32_bf16 v[100:103], v[156:159], v[186:189], v[100:103]
	v_mfma_f32_16x16x32_bf16 v[96:99], v[170:173], v[186:189], v[96:99]
	v_mfma_f32_16x16x32_bf16 v[84:87], v[156:159], v[194:197], v[84:87]
	v_mfma_f32_16x16x32_bf16 v[80:83], v[170:173], v[194:197], v[80:83]
	v_mfma_f32_16x16x32_bf16 v[68:71], v[156:159], v[202:205], v[68:71]
	v_mfma_f32_16x16x32_bf16 v[64:67], v[170:173], v[202:205], v[64:67]
	v_mfma_f32_16x16x32_bf16 v[116:119], v[162:165], v[182:185], v[116:119]
	v_mfma_f32_16x16x32_bf16 v[112:115], v[174:177], v[182:185], v[112:115]
	v_mfma_f32_16x16x32_bf16 v[100:103], v[162:165], v[190:193], v[100:103]
	v_mfma_f32_16x16x32_bf16 v[96:99], v[174:177], v[190:193], v[96:99]
	v_mfma_f32_16x16x32_bf16 v[84:87], v[162:165], v[198:201], v[84:87]
	v_mfma_f32_16x16x32_bf16 v[80:83], v[174:177], v[198:201], v[80:83]
	v_mfma_f32_16x16x32_bf16 v[68:71], v[162:165], v[206:209], v[68:71]
	v_mfma_f32_16x16x32_bf16 v[64:67], v[174:177], v[206:209], v[64:67]
	s_setprio 0
	s_barrier
	s_add_i32 s78, s78, s2
	v_lshl_add_u64 v[210:211], s[72:73], 0, v[160:161]
	s_mov_b32 m0, s78
	ds_read_b128 v[178:181], v168 offset:16384
	ds_read_b128 v[182:185], v168 offset:17408
	ds_read_b128 v[186:189], v168 offset:18432
	ds_read_b128 v[190:193], v168 offset:19456
	ds_read_b128 v[194:197], v168 offset:20480
	ds_read_b128 v[198:201], v168 offset:21504
	ds_read_b128 v[202:205], v168 offset:22528
	ds_read_b128 v[206:209], v168 offset:23552
	global_load_lds_dwordx4 v[210:211], off
	s_add_i32 m0, s78, 0x2000
	s_add_u32 s78, s72, 0x40000
	v_lshl_add_u64 v[212:213], s[72:73], 0, v[128:129]
	s_addc_u32 s79, s73, 0
	s_add_i32 s23, s23, s2
	global_load_lds_dwordx4 v[212:213], off
	v_lshl_add_u64 v[214:215], s[78:79], 0, v[160:161]
	s_mov_b32 m0, s23
	v_lshl_add_u64 v[216:217], s[74:75], 0, v[130:131]
	global_load_lds_dwordx4 v[214:215], off
	v_lshl_add_u64 v[214:215], s[78:79], 0, v[128:129]
	s_add_i32 m0, s23, 0x2000
	s_nop 0
	global_load_lds_dwordx4 v[214:215], off
	v_lshl_add_u64 v[214:215], s[74:75], 0, v[132:133]
	s_mov_b32 m0, s3
	s_nop 0
	global_load_lds_dwordx4 v[214:215], off
	s_mov_b32 m0, s28
	s_nop 0
	global_load_lds_dwordx4 v[216:217], off
	s_waitcnt vmcnt(8)
	s_waitcnt lgkmcnt(0)
	s_barrier
; #define PG8_STAGE(bufoff, gbase, voff) do { _Pragma("unroll") for (int _i = 0; _i < 2; ++_i) \
;         __builtin_amdgcn_global_load_lds((const unsigned*)((const char*)(gbase) + (voff)[_i]), (PG8_LAS unsigned*)(lds + (bufoff) + ldsw + _i * 8192), 16, 0, 0); } while (0)
; #define PG8_LDA(dst, b, h) do { _Pragma("unroll") for (int m = 0; m < 4; ++m) _Pragma("unroll") for (int k = 0; k < 2; ++k) dst[m][k] = *(const PG8_LAS bf16x8*)(lds + PG8_SA(b, h) + aoff + m * 2048 + k * 1024); } while (0)
; #define PG8_LDB(dst, b, h) do { _Pragma("unroll") for (int n = 0; n < 2; ++n) _Pragma("unroll") for (int k = 0; k < 2; ++k) dst[n][k] = *(const PG8_LAS bf16x8*)(lds + PG8_SB(b, h) + boff + n * 2048 + k * 1024); } while (0)
; #define PG8_MMA(ai, bj, At, Bt) do { __builtin_amdgcn_s_setprio(1); _Pragma("unroll") for (int m = 0; m < 4; ++m) _Pragma("unroll") for (int n = 0; n < 2; ++n) _Pragma("unroll") for (int k = 0; k < 2; ++k) \
;         acc[ai][bj][m][n] = __builtin_amdgcn_mfma_f32_16x16x32_bf16(Bt[n][k], At[m][k], acc[ai][bj][m][n], 0, 0, 0); __builtin_amdgcn_s_setprio(0); } while (0)
; #define PG8_WAIT_V(n) asm volatile("s_waitcnt vmcnt(" #n ")" ::: "memory")
; #define PG8_WAIT_L(n) asm volatile("s_waitcnt lgkmcnt(" #n ")" ::: "memory")
; #define PG8_BAR __builtin_amdgcn_s_barrier()
; #define PG8_SCHED __builtin_amdgcn_sched_barrier(0)
; template <class Epi, class Sched, bool ALIGN_EPI = false, bool SP2 = false>
; __device__ __forceinline__ void gemm_phase(PG8_LAS unsigned char* lds, const Gemm g, const Sched& S, const Epi& E) {
;     ...
;             PG8_WAIT_V(8); PG8_WAIT_L(0); PG8_BAR; PG8_MMA(1, 0, At, B0); PG8_MMA(1, 1, At, B1); PG8_BAR; PG8_SCHED;
;             PG8_LDB(B0, 1, 0); PG8_LDB(B1, 1, 1); PG8_SCHED; PG8_LDA(At, 1, 0); PG8_STAGE(PG8_SA(0, 1), a2 + hstep, voffA);
;             PG8_WAIT_V(8); PG8_WAIT_L(0); PG8_BAR; PG8_MMA(0, 0, At, B0); PG8_MMA(0, 1, At, B1); PG8_BAR; PG8_SCHED;
	s_setprio 1
	v_mfma_f32_16x16x32_bf16 v[60:63], v[140:143], v[178:181], v[60:63]
	v_mfma_f32_16x16x32_bf16 v[56:59], v[148:151], v[178:181], v[56:59]
	v_mfma_f32_16x16x32_bf16 v[44:47], v[140:143], v[186:189], v[44:47]
	v_mfma_f32_16x16x32_bf16 v[40:43], v[148:151], v[186:189], v[40:43]
	v_mfma_f32_16x16x32_bf16 v[28:31], v[140:143], v[194:197], v[28:31]
	v_mfma_f32_16x16x32_bf16 v[24:27], v[148:151], v[194:197], v[24:27]
	v_mfma_f32_16x16x32_bf16 v[12:15], v[140:143], v[202:205], v[12:15]
	v_mfma_f32_16x16x32_bf16 v[8:11], v[148:151], v[202:205], v[8:11]
	v_mfma_f32_16x16x32_bf16 v[60:63], v[144:147], v[182:185], v[60:63]
	v_mfma_f32_16x16x32_bf16 v[56:59], v[152:155], v[182:185], v[56:59]
	v_mfma_f32_16x16x32_bf16 v[44:47], v[144:147], v[190:193], v[44:47]
	v_mfma_f32_16x16x32_bf16 v[40:43], v[152:155], v[190:193], v[40:43]
	v_mfma_f32_16x16x32_bf16 v[28:31], v[144:147], v[198:201], v[28:31]
	v_mfma_f32_16x16x32_bf16 v[24:27], v[152:155], v[198:201], v[24:27]
	v_mfma_f32_16x16x32_bf16 v[12:15], v[144:147], v[206:209], v[12:15]
	v_mfma_f32_16x16x32_bf16 v[8:11], v[152:155], v[206:209], v[8:11]
	s_setprio 0
	s_setprio 1
	v_mfma_f32_16x16x32_bf16 v[52:55], v[156:159], v[178:181], v[52:55]
	v_mfma_f32_16x16x32_bf16 v[48:51], v[170:173], v[178:181], v[48:51]
	v_mfma_f32_16x16x32_bf16 v[36:39], v[156:159], v[186:189], v[36:39]
	v_mfma_f32_16x16x32_bf16 v[32:35], v[170:173], v[186:189], v[32:35]
	v_mfma_f32_16x16x32_bf16 v[20:23], v[156:159], v[194:197], v[20:23]
	v_mfma_f32_16x16x32_bf16 v[16:19], v[170:173], v[194:197], v[16:19]
	v_mfma_f32_16x16x32_bf16 v[4:7], v[156:159], v[202:205], v[4:7]
	v_mfma_f32_16x16x32_bf16 v[0:3], v[170:173], v[202:205], v[0:3]
	v_mfma_f32_16x16x32_bf16 v[52:55], v[162:165], v[182:185], v[52:55]
	v_mfma_f32_16x16x32_bf16 v[48:51], v[174:177], v[182:185], v[48:51]
	v_mfma_f32_16x16x32_bf16 v[36:39], v[162:165], v[190:193], v[36:39]
	v_mfma_f32_16x16x32_bf16 v[32:35], v[174:177], v[190:193], v[32:35]
	v_mfma_f32_16x16x32_bf16 v[20:23], v[162:165], v[198:201], v[20:23]
	v_mfma_f32_16x16x32_bf16 v[16:19], v[174:177], v[198:201], v[16:19]
	v_mfma_f32_16x16x32_bf16 v[4:7], v[162:165], v[206:209], v[4:7]
	v_mfma_f32_16x16x32_bf16 v[0:3], v[174:177], v[206:209], v[0:3]
	s_setprio 0
	s_barrier
	s_add_i32 s23, 0, 0x18000
	v_add_u32_e32 v138, s23, v166
	s_add_i32 s78, 0, 0x1c000
	ds_read_b128 v[140:143], v138
	ds_read_b128 v[144:147], v138 offset:1024
	ds_read_b128 v[148:151], v138 offset:2048
	ds_read_b128 v[152:155], v138 offset:3072
	v_add_u32_e32 v138, s78, v166
	ds_read_b128 v[156:159], v138
	ds_read_b128 v[162:165], v138 offset:1024
	ds_read_b128 v[170:173], v138 offset:2048
	ds_read_b128 v[174:177], v138 offset:3072
	s_add_u32 s74, s74, 0x40000
	s_addc_u32 s75, s75, 0
	s_mov_b32 m0, s29
	v_lshl_add_u64 v[222:223], s[74:75], 0, v[132:133]
	ds_read_b128 v[178:181], v168 offset:32768
	ds_read_b128 v[182:185], v168 offset:33792
	ds_read_b128 v[186:189], v168 offset:34816
	ds_read_b128 v[190:193], v168 offset:35840
	ds_read_b128 v[194:197], v168 offset:36864
	ds_read_b128 v[198:201], v168 offset:37888
	ds_read_b128 v[202:205], v168 offset:38912
	ds_read_b128 v[206:209], v168 offset:39936
	global_load_lds_dwordx4 v[222:223], off
	v_lshl_add_u64 v[222:223], s[74:75], 0, v[130:131]
	s_mov_b32 m0, s33
	s_nop 0
	global_load_lds_dwordx4 v[222:223], off
	s_waitcnt vmcnt(8)
	s_waitcnt lgkmcnt(0)
	s_barrier
	s_setprio 1
	v_mfma_f32_16x16x32_bf16 v[124:127], v[140:143], v[178:181], v[124:127]
	v_mfma_f32_16x16x32_bf16 v[120:123], v[148:151], v[178:181], v[120:123]
	v_mfma_f32_16x16x32_bf16 v[108:111], v[140:143], v[186:189], v[108:111]
	v_mfma_f32_16x16x32_bf16 v[104:107], v[148:151], v[186:189], v[104:107]
	v_mfma_f32_16x16x32_bf16 v[92:95], v[140:143], v[194:197], v[92:95]
	v_mfma_f32_16x16x32_bf16 v[88:91], v[148:151], v[194:197], v[88:91]
	v_mfma_f32_16x16x32_bf16 v[76:79], v[140:143], v[202:205], v[76:79]
	v_mfma_f32_16x16x32_bf16 v[72:75], v[148:151], v[202:205], v[72:75]
	v_mfma_f32_16x16x32_bf16 v[124:127], v[144:147], v[182:185], v[124:127]
	v_mfma_f32_16x16x32_bf16 v[120:123], v[152:155], v[182:185], v[120:123]
	v_mfma_f32_16x16x32_bf16 v[108:111], v[144:147], v[190:193], v[108:111]
	v_mfma_f32_16x16x32_bf16 v[104:107], v[152:155], v[190:193], v[104:107]
	v_mfma_f32_16x16x32_bf16 v[92:95], v[144:147], v[198:201], v[92:95]
	v_mfma_f32_16x16x32_bf16 v[88:91], v[152:155], v[198:201], v[88:91]
	v_mfma_f32_16x16x32_bf16 v[76:79], v[144:147], v[206:209], v[76:79]
	v_mfma_f32_16x16x32_bf16 v[72:75], v[152:155], v[206:209], v[72:75]
	s_setprio 0
	s_setprio 1
	v_mfma_f32_16x16x32_bf16 v[116:119], v[156:159], v[178:181], v[116:119]
	v_mfma_f32_16x16x32_bf16 v[112:115], v[170:173], v[178:181], v[112:115]
	v_mfma_f32_16x16x32_bf16 v[100:103], v[156:159], v[186:189], v[100:103]
	v_mfma_f32_16x16x32_bf16 v[96:99], v[170:173], v[186:189], v[96:99]
	v_mfma_f32_16x16x32_bf16 v[84:87], v[156:159], v[194:197], v[84:87]
	v_mfma_f32_16x16x32_bf16 v[80:83], v[170:173], v[194:197], v[80:83]
	v_mfma_f32_16x16x32_bf16 v[68:71], v[156:159], v[202:205], v[68:71]
	v_mfma_f32_16x16x32_bf16 v[64:67], v[170:173], v[202:205], v[64:67]
	v_mfma_f32_16x16x32_bf16 v[116:119], v[162:165], v[182:185], v[116:119]
	v_mfma_f32_16x16x32_bf16 v[112:115], v[174:177], v[182:185], v[112:115]
	v_mfma_f32_16x16x32_bf16 v[100:103], v[162:165], v[190:193], v[100:103]
	v_mfma_f32_16x16x32_bf16 v[96:99], v[174:177], v[190:193], v[96:99]
	v_mfma_f32_16x16x32_bf16 v[84:87], v[162:165], v[198:201], v[84:87]
	v_mfma_f32_16x16x32_bf16 v[80:83], v[174:177], v[198:201], v[80:83]
	v_mfma_f32_16x16x32_bf16 v[68:71], v[162:165], v[206:209], v[68:71]
	v_mfma_f32_16x16x32_bf16 v[64:67], v[174:177], v[206:209], v[64:67]
	s_setprio 0
	s_barrier
; #define PG8_STAGE(bufoff, gbase, voff) do { _Pragma("unroll") for (int _i = 0; _i < 2; ++_i) \
;         __builtin_amdgcn_global_load_lds((const unsigned*)((const char*)(gbase) + (voff)[_i]), (PG8_LAS unsigned*)(lds + (bufoff) + ldsw + _i * 8192), 16, 0, 0); } while (0)
; #define PG8_LDA(dst, b, h) do { _Pragma("unroll") for (int m = 0; m < 4; ++m) _Pragma("unroll") for (int k = 0; k < 2; ++k) dst[m][k] = *(const PG8_LAS bf16x8*)(lds + PG8_SA(b, h) + aoff + m * 2048 + k * 1024); } while (0)
; #define PG8_MMA(ai, bj, At, Bt) do { __builtin_amdgcn_s_setprio(1); _Pragma("unroll") for (int m = 0; m < 4; ++m) _Pragma("unroll") for (int n = 0; n < 2; ++n) _Pragma("unroll") for (int k = 0; k < 2; ++k) \
;         acc[ai][bj][m][n] = __builtin_amdgcn_mfma_f32_16x16x32_bf16(Bt[n][k], At[m][k], acc[ai][bj][m][n], 0, 0, 0); __builtin_amdgcn_s_setprio(0); } while (0)
; #define PG8_WAIT_V(n) asm volatile("s_waitcnt vmcnt(" #n ")" ::: "memory")
; #define PG8_WAIT_L(n) asm volatile("s_waitcnt lgkmcnt(" #n ")" ::: "memory")
; #define PG8_BAR __builtin_amdgcn_s_barrier()
; #define PG8_SCHED __builtin_amdgcn_sched_barrier(0)
; template <class Epi, class Sched, bool ALIGN_EPI = false, bool SP2 = false>
; __device__ __forceinline__ void gemm_phase(PG8_LAS unsigned char* lds, const Gemm g, const Sched& S, const Epi& E) {
;     ...
;             PG8_LDA(At, 1, 1); PG8_STAGE(PG8_SB(1, 0), b3, voffB); PG8_STAGE(PG8_SB(1, 1), b3 + hstep, voffB); PG8_STAGE(PG8_SA(1, 0), a3, voffA);
;             PG8_WAIT_V(8); PG8_WAIT_L(0); PG8_BAR; PG8_MMA(1, 0, At, B0); PG8_MMA(1, 1, At, B1); PG8_BAR; PG8_SCHED;
	s_add_i32 s23, s23, s2
	v_lshl_add_u64 v[210:211], v[210:211], 0, s[24:25]
	s_mov_b32 m0, s23
	ds_read_b128 v[178:181], v168 offset:49152
	ds_read_b128 v[182:185], v168 offset:50176
	ds_read_b128 v[186:189], v168 offset:51200
	ds_read_b128 v[190:193], v168 offset:52224
	ds_read_b128 v[194:197], v168 offset:53248
	ds_read_b128 v[198:201], v168 offset:54272
	ds_read_b128 v[202:205], v168 offset:55296
	ds_read_b128 v[206:209], v168 offset:56320
	global_load_lds_dwordx4 v[210:211], off
	s_add_i32 m0, s23, 0x2000
	s_add_u32 s72, s72, 0x40080
	v_lshl_add_u64 v[210:211], v[212:213], 0, s[24:25]
	s_addc_u32 s73, s73, 0
	s_add_i32 s23, s78, s2
	global_load_lds_dwordx4 v[210:211], off
	v_lshl_add_u64 v[210:211], s[72:73], 0, v[160:161]
	s_mov_b32 m0, s23
	s_nop 0
	global_load_lds_dwordx4 v[210:211], off
	v_lshl_add_u64 v[210:211], s[72:73], 0, v[128:129]
	s_add_i32 m0, s23, 0x2000
	s_nop 0
	global_load_lds_dwordx4 v[210:211], off
	v_lshl_add_u64 v[210:211], v[214:215], 0, s[24:25]
	s_mov_b32 m0, s44
	s_nop 0
	global_load_lds_dwordx4 v[210:211], off
	v_lshl_add_u64 v[210:211], v[216:217], 0, s[24:25]
	s_mov_b32 m0, s50
	s_nop 0
	global_load_lds_dwordx4 v[210:211], off
	s_waitcnt vmcnt(8)
	s_waitcnt lgkmcnt(0)
	s_barrier
	s_setprio 1
	v_mfma_f32_16x16x32_bf16 v[60:63], v[140:143], v[178:181], v[60:63]
	v_mfma_f32_16x16x32_bf16 v[56:59], v[148:151], v[178:181], v[56:59]
	v_mfma_f32_16x16x32_bf16 v[44:47], v[140:143], v[186:189], v[44:47]
	v_mfma_f32_16x16x32_bf16 v[40:43], v[148:151], v[186:189], v[40:43]
	v_mfma_f32_16x16x32_bf16 v[28:31], v[140:143], v[194:197], v[28:31]
	v_mfma_f32_16x16x32_bf16 v[24:27], v[148:151], v[194:197], v[24:27]
	v_mfma_f32_16x16x32_bf16 v[12:15], v[140:143], v[202:205], v[12:15]
	v_mfma_f32_16x16x32_bf16 v[8:11], v[148:151], v[202:205], v[8:11]
	v_mfma_f32_16x16x32_bf16 v[60:63], v[144:147], v[182:185], v[60:63]
	v_mfma_f32_16x16x32_bf16 v[56:59], v[152:155], v[182:185], v[56:59]
	v_mfma_f32_16x16x32_bf16 v[44:47], v[144:147], v[190:193], v[44:47]
	v_mfma_f32_16x16x32_bf16 v[40:43], v[152:155], v[190:193], v[40:43]
	v_mfma_f32_16x16x32_bf16 v[28:31], v[144:147], v[198:201], v[28:31]
	v_mfma_f32_16x16x32_bf16 v[24:27], v[152:155], v[198:201], v[24:27]
	v_mfma_f32_16x16x32_bf16 v[12:15], v[144:147], v[206:209], v[12:15]
	v_mfma_f32_16x16x32_bf16 v[8:11], v[152:155], v[206:209], v[8:11]
	s_setprio 0
	s_setprio 1
	v_mfma_f32_16x16x32_bf16 v[52:55], v[156:159], v[178:181], v[52:55]
	v_mfma_f32_16x16x32_bf16 v[48:51], v[170:173], v[178:181], v[48:51]
	v_mfma_f32_16x16x32_bf16 v[36:39], v[156:159], v[186:189], v[36:39]
	v_mfma_f32_16x16x32_bf16 v[32:35], v[170:173], v[186:189], v[32:35]
	v_mfma_f32_16x16x32_bf16 v[20:23], v[156:159], v[194:197], v[20:23]
	v_mfma_f32_16x16x32_bf16 v[16:19], v[170:173], v[194:197], v[16:19]
	v_mfma_f32_16x16x32_bf16 v[4:7], v[156:159], v[202:205], v[4:7]
	v_mfma_f32_16x16x32_bf16 v[0:3], v[170:173], v[202:205], v[0:3]
	v_mfma_f32_16x16x32_bf16 v[52:55], v[162:165], v[182:185], v[52:55]
	v_mfma_f32_16x16x32_bf16 v[48:51], v[174:177], v[182:185], v[48:51]
	v_mfma_f32_16x16x32_bf16 v[36:39], v[162:165], v[190:193], v[36:39]
	v_mfma_f32_16x16x32_bf16 v[32:35], v[174:177], v[190:193], v[32:35]
	v_mfma_f32_16x16x32_bf16 v[20:23], v[162:165], v[198:201], v[20:23]
	v_mfma_f32_16x16x32_bf16 v[16:19], v[174:177], v[198:201], v[16:19]
	v_mfma_f32_16x16x32_bf16 v[4:7], v[162:165], v[206:209], v[4:7]
	v_mfma_f32_16x16x32_bf16 v[0:3], v[174:177], v[206:209], v[0:3]
	s_setprio 0
	s_barrier
	s_add_i32 s22, s22, 2
	s_add_u32 s70, s70, 0x100
	s_addc_u32 s71, s71, 0
	s_add_u32 s58, s58, 0x100
	s_addc_u32 s59, s59, 0
	s_cmp_gt_u32 s22, 13
	s_cbranch_scc0 .LBB0_166
	s_and_b64 vcc, exec, s[10:11]
	s_cbranch_vccz .LBB0_169
	s_barrier

; #define PG8_STAGE(bufoff, gbase, voff) do { _Pragma("unroll") for (int _i = 0; _i < 2; ++_i) \
;         __builtin_amdgcn_global_load_lds((const unsigned*)((const char*)(gbase) + (voff)[_i]), (PG8_LAS unsigned*)(lds + (bufoff) + ldsw + _i * 8192), 16, 0, 0); } while (0)
; #define PG8_LDA(dst, b, h) do { _Pragma("unroll") for (int m = 0; m < 4; ++m) _Pragma("unroll") for (int k = 0; k < 2; ++k) dst[m][k] = *(const PG8_LAS bf16x8*)(lds + PG8_SA(b, h) + aoff + m * 2048 + k * 1024); } while (0)
; #define PG8_LDB(dst, b, h) do { _Pragma("unroll") for (int n = 0; n < 2; ++n) _Pragma("unroll") for (int k = 0; k < 2; ++k) dst[n][k] = *(const PG8_LAS bf16x8*)(lds + PG8_SB(b, h) + boff + n * 2048 + k * 1024); } while (0)
; #define PG8_MMA(ai, bj, At, Bt) do { __builtin_amdgcn_s_setprio(1); _Pragma("unroll") for (int m = 0; m < 4; ++m) _Pragma("unroll") for (int n = 0; n < 2; ++n) _Pragma("unroll") for (int k = 0; k < 2; ++k) \
;         acc[ai][bj][m][n] = __builtin_amdgcn_mfma_f32_16x16x32_bf16(Bt[n][k], At[m][k], acc[ai][bj][m][n], 0, 0, 0); __builtin_amdgcn_s_setprio(0); } while (0)
; #define PG8_WAIT_V(n) asm volatile("s_waitcnt vmcnt(" #n ")" ::: "memory")
; #define PG8_WAIT_L(n) asm volatile("s_waitcnt lgkmcnt(" #n ")" ::: "memory")
; template <class Epi, class Sched, bool ALIGN_EPI = false, bool SP2 = false>
; __device__ __forceinline__ void gemm_phase(PG8_LAS unsigned char* lds, const Gemm g, const Sched& S, const Epi& E) {
;     ...
;             const bool last = (t == nt - 2);
;             const char* a1 = cA + (size_t)(t + 1) * kstep;
;             const char* a2 = last ? nA : cA + (size_t)(t + 2) * kstep; const char* b2 = last ? nB : cB + (size_t)(t + 2) * kstep;
;             const char* a3 = a2 + kstep; const char* b3 = b2 + kstep;
;             if (last && has_next) S.a_ready(nxt);
;             if constexpr (SP2) {
;             PG8_LDB(B0, 0, 0); PG8_LDB(B1, 0, 1); PG8_SCHED; PG8_LDA(At, 0, 0); PG8_STAGE(PG8_SA(1, 1), a1 + hstep, voffA);
;             PG8_WAIT_V(8); PG8_WAIT_L(0); PG8_BAR; PG8_MMA(0, 0, At, B0); PG8_MMA(0, 1, At, B1); PG8_BAR; PG8_SCHED;
;             PG8_LDA(At, 0, 1); PG8_STAGE(PG8_SB(0, 0), b2, voffB); PG8_STAGE(PG8_SB(0, 1), b2 + hstep, voffB); PG8_STAGE(PG8_SA(0, 0), a2, voffA);
;             PG8_WAIT_V(8); PG8_WAIT_L(0); PG8_BAR; PG8_MMA(1, 0, At, B0); PG8_MMA(1, 1, At, B1); PG8_BAR; PG8_SCHED;
.LBB0_619:
	s_add_u32 s78, s76, 0x100
	s_addc_u32 s79, s77, 0
	s_add_i32 s62, 0, 0x10000
	s_cmp_eq_u32 s23, 12
	s_cselect_b32 vcc_hi, s57, s79
	s_cselect_b32 vcc_lo, s71, s78
	s_cselect_b32 s81, s69, s22
	s_cselect_b32 s80, s58, s59
	s_add_i32 s63, 0, 0x14000
	v_add_u32_e32 v88, s62, v175
	v_add_u32_e32 v158, s63, v175
	ds_read_b128 v[68:71], v88
	ds_read_b128 v[76:79], v88 offset:1024
	ds_read_b128 v[84:87], v88 offset:2048
	ds_read_b128 v[88:91], v88 offset:3072
	ds_read_b128 v[150:153], v158
	ds_read_b128 v[154:157], v158 offset:1024
	ds_read_b128 v[162:165], v158 offset:2048
	ds_read_b128 v[166:169], v158 offset:3072
	v_lshl_add_u64 v[158:159], s[76:77], 0, v[146:147]
	s_add_i32 m0, s5, 0xc000
	ds_read_b128 v[170:173], v179
	ds_read_b128 v[180:183], v179 offset:1024
	ds_read_b128 v[184:187], v179 offset:2048
	ds_read_b128 v[188:191], v179 offset:3072
	ds_read_b128 v[192:195], v179 offset:4096
	ds_read_b128 v[196:199], v179 offset:5120
	ds_read_b128 v[200:203], v179 offset:6144
	ds_read_b128 v[204:207], v179 offset:7168
	global_load_lds_dwordx4 v[158:159], off
	v_lshl_add_u64 v[158:159], s[76:77], 0, v[148:149]
	s_add_i32 m0, s5, 0xe000
	s_nop 0
	global_load_lds_dwordx4 v[158:159], off
	s_waitcnt vmcnt(8)
	s_waitcnt lgkmcnt(0)
	s_barrier
	s_setprio 1
	v_mfma_f32_16x16x32_bf16 v[140:143], v[68:71], v[170:173], v[140:143]
	v_mfma_f32_16x16x32_bf16 v[136:139], v[84:87], v[170:173], v[136:139]
	v_mfma_f32_16x16x32_bf16 v[124:127], v[68:71], v[184:187], v[124:127]
	v_mfma_f32_16x16x32_bf16 v[120:123], v[84:87], v[184:187], v[120:123]
	v_mfma_f32_16x16x32_bf16 v[108:111], v[68:71], v[192:195], v[108:111]
	v_mfma_f32_16x16x32_bf16 v[104:107], v[84:87], v[192:195], v[104:107]
	v_mfma_f32_16x16x32_bf16 v[92:95], v[68:71], v[200:203], v[92:95]
	v_mfma_f32_16x16x32_bf16 v[80:83], v[84:87], v[200:203], v[80:83]
	v_mfma_f32_16x16x32_bf16 v[140:143], v[76:79], v[180:183], v[140:143]
	v_mfma_f32_16x16x32_bf16 v[136:139], v[88:91], v[180:183], v[136:139]
	v_mfma_f32_16x16x32_bf16 v[124:127], v[76:79], v[188:191], v[124:127]
	v_mfma_f32_16x16x32_bf16 v[120:123], v[88:91], v[188:191], v[120:123]
	v_mfma_f32_16x16x32_bf16 v[108:111], v[76:79], v[196:199], v[108:111]
	v_mfma_f32_16x16x32_bf16 v[104:107], v[88:91], v[196:199], v[104:107]
	v_mfma_f32_16x16x32_bf16 v[92:95], v[76:79], v[204:207], v[92:95]
	v_mfma_f32_16x16x32_bf16 v[80:83], v[88:91], v[204:207], v[80:83]
	s_setprio 0
	s_setprio 1
	v_mfma_f32_16x16x32_bf16 v[132:135], v[150:153], v[170:173], v[132:135]
	v_mfma_f32_16x16x32_bf16 v[128:131], v[162:165], v[170:173], v[128:131]
	v_mfma_f32_16x16x32_bf16 v[116:119], v[150:153], v[184:187], v[116:119]
	v_mfma_f32_16x16x32_bf16 v[112:115], v[162:165], v[184:187], v[112:115]
	v_mfma_f32_16x16x32_bf16 v[100:103], v[150:153], v[192:195], v[100:103]
	v_mfma_f32_16x16x32_bf16 v[96:99], v[162:165], v[192:195], v[96:99]
	v_mfma_f32_16x16x32_bf16 v[72:75], v[150:153], v[200:203], v[72:75]
	v_mfma_f32_16x16x32_bf16 v[64:67], v[162:165], v[200:203], v[64:67]
	v_mfma_f32_16x16x32_bf16 v[132:135], v[154:157], v[180:183], v[132:135]
	v_mfma_f32_16x16x32_bf16 v[128:131], v[166:169], v[180:183], v[128:131]
	v_mfma_f32_16x16x32_bf16 v[116:119], v[154:157], v[188:191], v[116:119]
	v_mfma_f32_16x16x32_bf16 v[112:115], v[166:169], v[188:191], v[112:115]
	v_mfma_f32_16x16x32_bf16 v[100:103], v[154:157], v[196:199], v[100:103]
	v_mfma_f32_16x16x32_bf16 v[96:99], v[166:169], v[196:199], v[96:99]
	v_mfma_f32_16x16x32_bf16 v[72:75], v[154:157], v[204:207], v[72:75]
	v_mfma_f32_16x16x32_bf16 v[64:67], v[166:169], v[204:207], v[64:67]
	s_setprio 0
	s_barrier
	s_add_i32 s62, s62, s4
	v_lshl_add_u64 v[158:159], s[80:81], 0, v[160:161]
	s_mov_b32 m0, s62
	ds_read_b128 v[170:173], v179 offset:16384
	ds_read_b128 v[180:183], v179 offset:17408
	ds_read_b128 v[184:187], v179 offset:18432
	ds_read_b128 v[188:191], v179 offset:19456
	ds_read_b128 v[192:195], v179 offset:20480
	ds_read_b128 v[196:199], v179 offset:21504
	ds_read_b128 v[200:203], v179 offset:22528
	ds_read_b128 v[204:207], v179 offset:23552
	global_load_lds_dwordx4 v[158:159], off
	s_add_i32 m0, s62, 0x2000
	s_add_u32 s76, s80, 0x40000
	v_lshl_add_u64 v[208:209], s[80:81], 0, v[144:145]
	s_addc_u32 s77, s81, 0
	s_add_i32 s62, s63, s4
	global_load_lds_dwordx4 v[208:209], off
	v_lshl_add_u64 v[210:211], s[76:77], 0, v[160:161]
	s_mov_b32 m0, s62
	v_lshl_add_u64 v[212:213], vcc, 0, v[144:145]
	global_load_lds_dwordx4 v[210:211], off
	v_lshl_add_u64 v[210:211], s[76:77], 0, v[144:145]
	s_add_i32 m0, s62, 0x2000
	s_nop 0
	global_load_lds_dwordx4 v[210:211], off
	v_lshl_add_u64 v[210:211], vcc, 0, v[160:161]
	s_mov_b32 m0, s5
	s_nop 0
	global_load_lds_dwordx4 v[210:211], off
	s_mov_b32 m0, s33
	s_nop 0
	global_load_lds_dwordx4 v[212:213], off
	s_waitcnt vmcnt(8)
	s_waitcnt lgkmcnt(0)
	s_barrier
; #define PG8_STAGE(bufoff, gbase, voff) do { _Pragma("unroll") for (int _i = 0; _i < 2; ++_i) \
;         __builtin_amdgcn_global_load_lds((const unsigned*)((const char*)(gbase) + (voff)[_i]), (PG8_LAS unsigned*)(lds + (bufoff) + ldsw + _i * 8192), 16, 0, 0); } while (0)
; #define PG8_LDA(dst, b, h) do { _Pragma("unroll") for (int m = 0; m < 4; ++m) _Pragma("unroll") for (int k = 0; k < 2; ++k) dst[m][k] = *(const PG8_LAS bf16x8*)(lds + PG8_SA(b, h) + aoff + m * 2048 + k * 1024); } while (0)
; #define PG8_LDB(dst, b, h) do { _Pragma("unroll") for (int n = 0; n < 2; ++n) _Pragma("unroll") for (int k = 0; k < 2; ++k) dst[n][k] = *(const PG8_LAS bf16x8*)(lds + PG8_SB(b, h) + boff + n * 2048 + k * 1024); } while (0)
; #define PG8_MMA(ai, bj, At, Bt) do { __builtin_amdgcn_s_setprio(1); _Pragma("unroll") for (int m = 0; m < 4; ++m) _Pragma("unroll") for (int n = 0; n < 2; ++n) _Pragma("unroll") for (int k = 0; k < 2; ++k) \
;         acc[ai][bj][m][n] = __builtin_amdgcn_mfma_f32_16x16x32_bf16(Bt[n][k], At[m][k], acc[ai][bj][m][n], 0, 0, 0); __builtin_amdgcn_s_setprio(0); } while (0)
; #define PG8_WAIT_V(n) asm volatile("s_waitcnt vmcnt(" #n ")" ::: "memory")
; #define PG8_WAIT_L(n) asm volatile("s_waitcnt lgkmcnt(" #n ")" ::: "memory")
; #define PG8_BAR __builtin_amdgcn_s_barrier()
; #define PG8_SCHED __builtin_amdgcn_sched_barrier(0)
; template <class Epi, class Sched, bool ALIGN_EPI = false, bool SP2 = false>
; __device__ __forceinline__ void gemm_phase(PG8_LAS unsigned char* lds, const Gemm g, const Sched& S, const Epi& E) {
;     ...
;             PG8_WAIT_V(8); PG8_WAIT_L(0); PG8_BAR; PG8_MMA(1, 0, At, B0); PG8_MMA(1, 1, At, B1); PG8_BAR; PG8_SCHED;
;             PG8_LDB(B0, 1, 0); PG8_LDB(B1, 1, 1); PG8_SCHED; PG8_LDA(At, 1, 0); PG8_STAGE(PG8_SA(0, 1), a2 + hstep, voffA);
;             PG8_WAIT_V(8); PG8_WAIT_L(0); PG8_BAR; PG8_MMA(0, 0, At, B0); PG8_MMA(0, 1, At, B1); PG8_BAR; PG8_SCHED;
	s_setprio 1
	v_mfma_f32_16x16x32_bf16 v[60:63], v[68:71], v[170:173], v[60:63]
	v_mfma_f32_16x16x32_bf16 v[56:59], v[84:87], v[170:173], v[56:59]
	v_mfma_f32_16x16x32_bf16 v[44:47], v[68:71], v[184:187], v[44:47]
	v_mfma_f32_16x16x32_bf16 v[40:43], v[84:87], v[184:187], v[40:43]
	v_mfma_f32_16x16x32_bf16 v[28:31], v[68:71], v[192:195], v[28:31]
	v_mfma_f32_16x16x32_bf16 v[24:27], v[84:87], v[192:195], v[24:27]
	v_mfma_f32_16x16x32_bf16 v[12:15], v[68:71], v[200:203], v[12:15]
	v_mfma_f32_16x16x32_bf16 v[8:11], v[84:87], v[200:203], v[8:11]
	v_mfma_f32_16x16x32_bf16 v[60:63], v[76:79], v[180:183], v[60:63]
	v_mfma_f32_16x16x32_bf16 v[56:59], v[88:91], v[180:183], v[56:59]
	v_mfma_f32_16x16x32_bf16 v[44:47], v[76:79], v[188:191], v[44:47]
	v_mfma_f32_16x16x32_bf16 v[40:43], v[88:91], v[188:191], v[40:43]
	v_mfma_f32_16x16x32_bf16 v[28:31], v[76:79], v[196:199], v[28:31]
	v_mfma_f32_16x16x32_bf16 v[24:27], v[88:91], v[196:199], v[24:27]
	v_mfma_f32_16x16x32_bf16 v[12:15], v[76:79], v[204:207], v[12:15]
	v_mfma_f32_16x16x32_bf16 v[8:11], v[88:91], v[204:207], v[8:11]
	s_setprio 0
	s_setprio 1
	v_mfma_f32_16x16x32_bf16 v[52:55], v[150:153], v[170:173], v[52:55]
	v_mfma_f32_16x16x32_bf16 v[48:51], v[162:165], v[170:173], v[48:51]
	v_mfma_f32_16x16x32_bf16 v[36:39], v[150:153], v[184:187], v[36:39]
	v_mfma_f32_16x16x32_bf16 v[32:35], v[162:165], v[184:187], v[32:35]
	v_mfma_f32_16x16x32_bf16 v[20:23], v[150:153], v[192:195], v[20:23]
	v_mfma_f32_16x16x32_bf16 v[16:19], v[162:165], v[192:195], v[16:19]
	v_mfma_f32_16x16x32_bf16 v[4:7], v[150:153], v[200:203], v[4:7]
	v_mfma_f32_16x16x32_bf16 v[0:3], v[162:165], v[200:203], v[0:3]
	v_mfma_f32_16x16x32_bf16 v[52:55], v[154:157], v[180:183], v[52:55]
	v_mfma_f32_16x16x32_bf16 v[48:51], v[166:169], v[180:183], v[48:51]
	v_mfma_f32_16x16x32_bf16 v[36:39], v[154:157], v[188:191], v[36:39]
	v_mfma_f32_16x16x32_bf16 v[32:35], v[166:169], v[188:191], v[32:35]
	v_mfma_f32_16x16x32_bf16 v[20:23], v[154:157], v[196:199], v[20:23]
	v_mfma_f32_16x16x32_bf16 v[16:19], v[166:169], v[196:199], v[16:19]
	v_mfma_f32_16x16x32_bf16 v[4:7], v[154:157], v[204:207], v[4:7]
	v_mfma_f32_16x16x32_bf16 v[0:3], v[166:169], v[204:207], v[0:3]
	s_setprio 0
	s_barrier
	s_add_i32 s62, 0, 0x18000
	s_add_i32 s63, 0, 0x1c000
	v_add_u32_e32 v88, s62, v175
	v_add_u32_e32 v166, s63, v175
	ds_read_b128 v[68:71], v88
	ds_read_b128 v[76:79], v88 offset:1024
	ds_read_b128 v[84:87], v88 offset:2048
	ds_read_b128 v[88:91], v88 offset:3072
	ds_read_b128 v[150:153], v166
	ds_read_b128 v[154:157], v166 offset:1024
	ds_read_b128 v[162:165], v166 offset:2048
	ds_read_b128 v[166:169], v166 offset:3072
	s_add_u32 s76, vcc_lo, 0x40000
	s_addc_u32 s77, vcc_hi, 0
	s_mov_b32 m0, s35
	v_lshl_add_u64 v[214:215], s[76:77], 0, v[160:161]
	ds_read_b128 v[170:173], v179 offset:32768
	ds_read_b128 v[180:183], v179 offset:33792
	ds_read_b128 v[184:187], v179 offset:34816
	ds_read_b128 v[188:191], v179 offset:35840
	ds_read_b128 v[192:195], v179 offset:36864
	ds_read_b128 v[196:199], v179 offset:37888
	ds_read_b128 v[200:203], v179 offset:38912
	ds_read_b128 v[204:207], v179 offset:39936
	global_load_lds_dwordx4 v[214:215], off
	v_lshl_add_u64 v[214:215], s[76:77], 0, v[144:145]
	s_mov_b32 m0, s84
	s_nop 0
	global_load_lds_dwordx4 v[214:215], off
	s_waitcnt vmcnt(8)
	s_waitcnt lgkmcnt(0)
	s_barrier
	s_setprio 1
	v_mfma_f32_16x16x32_bf16 v[140:143], v[68:71], v[170:173], v[140:143]
	v_mfma_f32_16x16x32_bf16 v[136:139], v[84:87], v[170:173], v[136:139]
	v_mfma_f32_16x16x32_bf16 v[124:127], v[68:71], v[184:187], v[124:127]
	v_mfma_f32_16x16x32_bf16 v[120:123], v[84:87], v[184:187], v[120:123]
	v_mfma_f32_16x16x32_bf16 v[108:111], v[68:71], v[192:195], v[108:111]
	v_mfma_f32_16x16x32_bf16 v[104:107], v[84:87], v[192:195], v[104:107]
	v_mfma_f32_16x16x32_bf16 v[92:95], v[68:71], v[200:203], v[92:95]
	v_mfma_f32_16x16x32_bf16 v[80:83], v[84:87], v[200:203], v[80:83]
	v_mfma_f32_16x16x32_bf16 v[140:143], v[76:79], v[180:183], v[140:143]
	v_mfma_f32_16x16x32_bf16 v[136:139], v[88:91], v[180:183], v[136:139]
	v_mfma_f32_16x16x32_bf16 v[124:127], v[76:79], v[188:191], v[124:127]
	v_mfma_f32_16x16x32_bf16 v[120:123], v[88:91], v[188:191], v[120:123]
	v_mfma_f32_16x16x32_bf16 v[108:111], v[76:79], v[196:199], v[108:111]
	v_mfma_f32_16x16x32_bf16 v[104:107], v[88:91], v[196:199], v[104:107]
	v_mfma_f32_16x16x32_bf16 v[92:95], v[76:79], v[204:207], v[92:95]
	v_mfma_f32_16x16x32_bf16 v[80:83], v[88:91], v[204:207], v[80:83]
	s_setprio 0
	s_setprio 1
	v_mfma_f32_16x16x32_bf16 v[132:135], v[150:153], v[170:173], v[132:135]
	v_mfma_f32_16x16x32_bf16 v[128:131], v[162:165], v[170:173], v[128:131]
	v_mfma_f32_16x16x32_bf16 v[116:119], v[150:153], v[184:187], v[116:119]
	v_mfma_f32_16x16x32_bf16 v[112:115], v[162:165], v[184:187], v[112:115]
	v_mfma_f32_16x16x32_bf16 v[100:103], v[150:153], v[192:195], v[100:103]
	v_mfma_f32_16x16x32_bf16 v[96:99], v[162:165], v[192:195], v[96:99]
	v_mfma_f32_16x16x32_bf16 v[72:75], v[150:153], v[200:203], v[72:75]
	v_mfma_f32_16x16x32_bf16 v[64:67], v[162:165], v[200:203], v[64:67]
	v_mfma_f32_16x16x32_bf16 v[132:135], v[154:157], v[180:183], v[132:135]
	v_mfma_f32_16x16x32_bf16 v[128:131], v[166:169], v[180:183], v[128:131]
	v_mfma_f32_16x16x32_bf16 v[116:119], v[154:157], v[188:191], v[116:119]
	v_mfma_f32_16x16x32_bf16 v[112:115], v[166:169], v[188:191], v[112:115]
	v_mfma_f32_16x16x32_bf16 v[100:103], v[154:157], v[196:199], v[100:103]
	v_mfma_f32_16x16x32_bf16 v[96:99], v[166:169], v[196:199], v[96:99]
	v_mfma_f32_16x16x32_bf16 v[72:75], v[154:157], v[204:207], v[72:75]
	v_mfma_f32_16x16x32_bf16 v[64:67], v[166:169], v[204:207], v[64:67]
	s_setprio 0
	s_barrier
; #define PG8_STAGE(bufoff, gbase, voff) do { _Pragma("unroll") for (int _i = 0; _i < 2; ++_i) \
;         __builtin_amdgcn_global_load_lds((const unsigned*)((const char*)(gbase) + (voff)[_i]), (PG8_LAS unsigned*)(lds + (bufoff) + ldsw + _i * 8192), 16, 0, 0); } while (0)
; #define PG8_LDA(dst, b, h) do { _Pragma("unroll") for (int m = 0; m < 4; ++m) _Pragma("unroll") for (int k = 0; k < 2; ++k) dst[m][k] = *(const PG8_LAS bf16x8*)(lds + PG8_SA(b, h) + aoff + m * 2048 + k * 1024); } while (0)
; #define PG8_MMA(ai, bj, At, Bt) do { __builtin_amdgcn_s_setprio(1); _Pragma("unroll") for (int m = 0; m < 4; ++m) _Pragma("unroll") for (int n = 0; n < 2; ++n) _Pragma("unroll") for (int k = 0; k < 2; ++k) \
;         acc[ai][bj][m][n] = __builtin_amdgcn_mfma_f32_16x16x32_bf16(Bt[n][k], At[m][k], acc[ai][bj][m][n], 0, 0, 0); __builtin_amdgcn_s_setprio(0); } while (0)
; #define PG8_WAIT_V(n) asm volatile("s_waitcnt vmcnt(" #n ")" ::: "memory")
; #define PG8_WAIT_L(n) asm volatile("s_waitcnt lgkmcnt(" #n ")" ::: "memory")
; #define PG8_BAR __builtin_amdgcn_s_barrier()
; #define PG8_SCHED __builtin_amdgcn_sched_barrier(0)
; template <class Epi, class Sched, bool ALIGN_EPI = false, bool SP2 = false>
; __device__ __forceinline__ void gemm_phase(PG8_LAS unsigned char* lds, const Gemm g, const Sched& S, const Epi& E) {
;     ...
;             PG8_LDA(At, 1, 1); PG8_STAGE(PG8_SB(1, 0), b3, voffB); PG8_STAGE(PG8_SB(1, 1), b3 + hstep, voffB); PG8_STAGE(PG8_SA(1, 0), a3, voffA);
;             PG8_WAIT_V(8); PG8_WAIT_L(0); PG8_BAR; PG8_MMA(1, 0, At, B0); PG8_MMA(1, 1, At, B1); PG8_BAR; PG8_SCHED;
	s_add_i32 s62, s62, s4
	v_lshl_add_u64 v[158:159], v[158:159], 0, s[24:25]
	s_mov_b32 m0, s62
	ds_read_b128 v[170:173], v179 offset:49152
	ds_read_b128 v[180:183], v179 offset:50176
	ds_read_b128 v[184:187], v179 offset:51200
	ds_read_b128 v[188:191], v179 offset:52224
	ds_read_b128 v[192:195], v179 offset:53248
	ds_read_b128 v[196:199], v179 offset:54272
	ds_read_b128 v[200:203], v179 offset:55296
	ds_read_b128 v[204:207], v179 offset:56320
	global_load_lds_dwordx4 v[158:159], off
	s_add_i32 m0, s62, 0x2000
	s_add_u32 s76, s80, 0x40080
	v_lshl_add_u64 v[158:159], v[208:209], 0, s[24:25]
	s_addc_u32 s77, s81, 0
	s_add_i32 s62, s63, s4
	global_load_lds_dwordx4 v[158:159], off
	v_lshl_add_u64 v[158:159], s[76:77], 0, v[160:161]
	s_mov_b32 m0, s62
	s_nop 0
	global_load_lds_dwordx4 v[158:159], off
	v_lshl_add_u64 v[158:159], s[76:77], 0, v[144:145]
	s_add_i32 m0, s62, 0x2000
	s_nop 0
	global_load_lds_dwordx4 v[158:159], off
	v_lshl_add_u64 v[158:159], v[210:211], 0, s[24:25]
	s_mov_b32 m0, s50
	s_nop 0
	global_load_lds_dwordx4 v[158:159], off
	v_lshl_add_u64 v[158:159], v[212:213], 0, s[24:25]
	s_mov_b32 m0, s51
	s_nop 0
	global_load_lds_dwordx4 v[158:159], off
	s_waitcnt vmcnt(8)
	s_waitcnt lgkmcnt(0)
	s_barrier
	s_setprio 1
	v_mfma_f32_16x16x32_bf16 v[60:63], v[68:71], v[170:173], v[60:63]
	v_mfma_f32_16x16x32_bf16 v[56:59], v[84:87], v[170:173], v[56:59]
	v_mfma_f32_16x16x32_bf16 v[44:47], v[68:71], v[184:187], v[44:47]
	v_mfma_f32_16x16x32_bf16 v[40:43], v[84:87], v[184:187], v[40:43]
	v_mfma_f32_16x16x32_bf16 v[28:31], v[68:71], v[192:195], v[28:31]
	v_mfma_f32_16x16x32_bf16 v[24:27], v[84:87], v[192:195], v[24:27]
	v_mfma_f32_16x16x32_bf16 v[12:15], v[68:71], v[200:203], v[12:15]
	v_mfma_f32_16x16x32_bf16 v[8:11], v[84:87], v[200:203], v[8:11]
	v_mfma_f32_16x16x32_bf16 v[60:63], v[76:79], v[180:183], v[60:63]
	v_mfma_f32_16x16x32_bf16 v[56:59], v[88:91], v[180:183], v[56:59]
	v_mfma_f32_16x16x32_bf16 v[44:47], v[76:79], v[188:191], v[44:47]
	v_mfma_f32_16x16x32_bf16 v[40:43], v[88:91], v[188:191], v[40:43]
	v_mfma_f32_16x16x32_bf16 v[28:31], v[76:79], v[196:199], v[28:31]
	v_mfma_f32_16x16x32_bf16 v[24:27], v[88:91], v[196:199], v[24:27]
	v_mfma_f32_16x16x32_bf16 v[12:15], v[76:79], v[204:207], v[12:15]
	v_mfma_f32_16x16x32_bf16 v[8:11], v[88:91], v[204:207], v[8:11]
	s_setprio 0
	s_setprio 1
	v_mfma_f32_16x16x32_bf16 v[52:55], v[150:153], v[170:173], v[52:55]
	v_mfma_f32_16x16x32_bf16 v[48:51], v[162:165], v[170:173], v[48:51]
	v_mfma_f32_16x16x32_bf16 v[36:39], v[150:153], v[184:187], v[36:39]
	v_mfma_f32_16x16x32_bf16 v[32:35], v[162:165], v[184:187], v[32:35]
	v_mfma_f32_16x16x32_bf16 v[20:23], v[150:153], v[192:195], v[20:23]
	v_mfma_f32_16x16x32_bf16 v[16:19], v[162:165], v[192:195], v[16:19]
	v_mfma_f32_16x16x32_bf16 v[4:7], v[150:153], v[200:203], v[4:7]
	v_mfma_f32_16x16x32_bf16 v[0:3], v[162:165], v[200:203], v[0:3]
	v_mfma_f32_16x16x32_bf16 v[52:55], v[154:157], v[180:183], v[52:55]
	v_mfma_f32_16x16x32_bf16 v[48:51], v[166:169], v[180:183], v[48:51]
	v_mfma_f32_16x16x32_bf16 v[36:39], v[154:157], v[188:191], v[36:39]
	v_mfma_f32_16x16x32_bf16 v[32:35], v[166:169], v[188:191], v[32:35]
	v_mfma_f32_16x16x32_bf16 v[20:23], v[154:157], v[196:199], v[20:23]
	v_mfma_f32_16x16x32_bf16 v[16:19], v[166:169], v[196:199], v[16:19]
	v_mfma_f32_16x16x32_bf16 v[4:7], v[154:157], v[204:207], v[4:7]
	v_mfma_f32_16x16x32_bf16 v[0:3], v[166:169], v[204:207], v[0:3]
	s_setprio 0
	s_barrier
	s_add_i32 s23, s23, 2
	s_add_u32 s59, s59, 0x100
	s_addc_u32 s22, s22, 0
	s_cmp_gt_u32 s23, 13
	s_mov_b64 s[76:77], s[78:79]
	s_cbranch_scc0 .LBB0_619
	s_and_b64 vcc, exec, s[66:67]
	s_cbranch_vccz .LBB0_622
	s_barrier

; #define PG8_STAGE(bufoff, gbase, voff) do { _Pragma("unroll") for (int _i = 0; _i < 2; ++_i) \
;         __builtin_amdgcn_global_load_lds((const unsigned*)((const char*)(gbase) + (voff)[_i]), (PG8_LAS unsigned*)(lds + (bufoff) + ldsw + _i * 8192), 16, 0, 0); } while (0)
; #define PG8_LDA(dst, b, h) do { _Pragma("unroll") for (int m = 0; m < 4; ++m) _Pragma("unroll") for (int k = 0; k < 2; ++k) dst[m][k] = *(const PG8_LAS bf16x8*)(lds + PG8_SA(b, h) + aoff + m * 2048 + k * 1024); } while (0)
; #define PG8_LDB(dst, b, h) do { _Pragma("unroll") for (int n = 0; n < 2; ++n) _Pragma("unroll") for (int k = 0; k < 2; ++k) dst[n][k] = *(const PG8_LAS bf16x8*)(lds + PG8_SB(b, h) + boff + n * 2048 + k * 1024); } while (0)
; #define PG8_MMA(ai, bj, At, Bt) do { __builtin_amdgcn_s_setprio(1); _Pragma("unroll") for (int m = 0; m < 4; ++m) _Pragma("unroll") for (int n = 0; n < 2; ++n) _Pragma("unroll") for (int k = 0; k < 2; ++k) \
;         acc[ai][bj][m][n] = __builtin_amdgcn_mfma_f32_16x16x32_bf16(Bt[n][k], At[m][k], acc[ai][bj][m][n], 0, 0, 0); __builtin_amdgcn_s_setprio(0); } while (0)
; #define PG8_WAIT_V(n) asm volatile("s_waitcnt vmcnt(" #n ")" ::: "memory")
; #define PG8_WAIT_L(n) asm volatile("s_waitcnt lgkmcnt(" #n ")" ::: "memory")
; template <class Epi, class Sched, bool ALIGN_EPI = false, bool SP2 = false>
; __device__ __forceinline__ void gemm_phase(PG8_LAS unsigned char* lds, const Gemm g, const Sched& S, const Epi& E) {
;     ...
;             const bool last = (t == nt - 2);
;             const char* a1 = cA + (size_t)(t + 1) * kstep;
;             const char* a2 = last ? nA : cA + (size_t)(t + 2) * kstep; const char* b2 = last ? nB : cB + (size_t)(t + 2) * kstep;
;             const char* a3 = a2 + kstep; const char* b3 = b2 + kstep;
;             if (last && has_next) S.a_ready(nxt);
;             if constexpr (SP2) {
;             PG8_LDB(B0, 0, 0); PG8_LDB(B1, 0, 1); PG8_SCHED; PG8_LDA(At, 0, 0); PG8_STAGE(PG8_SA(1, 1), a1 + hstep, voffA);
;             PG8_WAIT_V(8); PG8_WAIT_L(0); PG8_BAR; PG8_MMA(0, 0, At, B0); PG8_MMA(0, 1, At, B1); PG8_BAR; PG8_SCHED;
;             PG8_LDA(At, 0, 1); PG8_STAGE(PG8_SB(0, 0), b2, voffB); PG8_STAGE(PG8_SB(0, 1), b2 + hstep, voffB); PG8_STAGE(PG8_SA(0, 0), a2, voffA);
;             PG8_WAIT_V(8); PG8_WAIT_L(0); PG8_BAR; PG8_MMA(1, 0, At, B0); PG8_MMA(1, 1, At, B1); PG8_BAR; PG8_SCHED;
.LBB0_703:
	s_add_u32 s23, s72, 0xfffc0080
	s_addc_u32 s56, s73, -1
	s_add_i32 s57, 0, 0x10000
	s_cmp_eq_u32 s22, 12
	s_cselect_b32 s77, s29, s56
	s_cselect_b32 s76, s34, s23
	s_cselect_b32 s75, s35, s51
	s_cselect_b32 s74, s44, s50
	s_add_i32 s23, 0, 0x14000
	v_add_u32_e32 v60, s57, v165
	v_add_u32_e32 v158, s23, v165
	ds_read_b128 v[48:51], v60
	ds_read_b128 v[52:55], v60 offset:1024
	ds_read_b128 v[56:59], v60 offset:2048
	ds_read_b128 v[60:63], v60 offset:3072
	ds_read_b128 v[154:157], v158
	ds_read_b128 v[170:173], v158 offset:1024
	ds_read_b128 v[174:177], v158 offset:2048
	ds_read_b128 v[178:181], v158 offset:3072
	v_lshl_add_u64 v[158:159], s[72:73], 0, v[150:151]
	s_add_i32 m0, s79, 0xc000
	ds_read_b128 v[182:185], v167
	ds_read_b128 v[186:189], v167 offset:1024
	ds_read_b128 v[190:193], v167 offset:2048
	ds_read_b128 v[194:197], v167 offset:3072
	ds_read_b128 v[198:201], v167 offset:4096
	ds_read_b128 v[202:205], v167 offset:5120
	ds_read_b128 v[206:209], v167 offset:6144
	ds_read_b128 v[210:213], v167 offset:7168
	global_load_lds_dwordx4 v[158:159], off
	v_lshl_add_u64 v[158:159], s[72:73], 0, v[152:153]
	s_add_i32 m0, s79, 0xe000
	s_nop 0
	global_load_lds_dwordx4 v[158:159], off
	s_waitcnt vmcnt(8)
	s_waitcnt lgkmcnt(0)
	s_barrier
	s_setprio 1
	v_mfma_f32_16x16x32_bf16 v[140:143], v[48:51], v[182:185], v[140:143]
	v_mfma_f32_16x16x32_bf16 v[136:139], v[56:59], v[182:185], v[136:139]
	v_mfma_f32_16x16x32_bf16 v[124:127], v[48:51], v[190:193], v[124:127]
	v_mfma_f32_16x16x32_bf16 v[120:123], v[56:59], v[190:193], v[120:123]
	v_mfma_f32_16x16x32_bf16 v[108:111], v[48:51], v[198:201], v[108:111]
	v_mfma_f32_16x16x32_bf16 v[104:107], v[56:59], v[198:201], v[104:107]
	v_mfma_f32_16x16x32_bf16 v[92:95], v[48:51], v[206:209], v[92:95]
	v_mfma_f32_16x16x32_bf16 v[88:91], v[56:59], v[206:209], v[88:91]
	v_mfma_f32_16x16x32_bf16 v[140:143], v[52:55], v[186:189], v[140:143]
	v_mfma_f32_16x16x32_bf16 v[136:139], v[60:63], v[186:189], v[136:139]
	v_mfma_f32_16x16x32_bf16 v[124:127], v[52:55], v[194:197], v[124:127]
	v_mfma_f32_16x16x32_bf16 v[120:123], v[60:63], v[194:197], v[120:123]
	v_mfma_f32_16x16x32_bf16 v[108:111], v[52:55], v[202:205], v[108:111]
	v_mfma_f32_16x16x32_bf16 v[104:107], v[60:63], v[202:205], v[104:107]
	v_mfma_f32_16x16x32_bf16 v[92:95], v[52:55], v[210:213], v[92:95]
	v_mfma_f32_16x16x32_bf16 v[88:91], v[60:63], v[210:213], v[88:91]
	s_setprio 0
	s_setprio 1
	v_mfma_f32_16x16x32_bf16 v[132:135], v[154:157], v[182:185], v[132:135]
	v_mfma_f32_16x16x32_bf16 v[128:131], v[174:177], v[182:185], v[128:131]
	v_mfma_f32_16x16x32_bf16 v[116:119], v[154:157], v[190:193], v[116:119]
	v_mfma_f32_16x16x32_bf16 v[112:115], v[174:177], v[190:193], v[112:115]
	v_mfma_f32_16x16x32_bf16 v[100:103], v[154:157], v[198:201], v[100:103]
	v_mfma_f32_16x16x32_bf16 v[96:99], v[174:177], v[198:201], v[96:99]
	v_mfma_f32_16x16x32_bf16 v[84:87], v[154:157], v[206:209], v[84:87]
	v_mfma_f32_16x16x32_bf16 v[80:83], v[174:177], v[206:209], v[80:83]
	v_mfma_f32_16x16x32_bf16 v[132:135], v[170:173], v[186:189], v[132:135]
	v_mfma_f32_16x16x32_bf16 v[128:131], v[178:181], v[186:189], v[128:131]
	v_mfma_f32_16x16x32_bf16 v[116:119], v[170:173], v[194:197], v[116:119]
	v_mfma_f32_16x16x32_bf16 v[112:115], v[178:181], v[194:197], v[112:115]
	v_mfma_f32_16x16x32_bf16 v[100:103], v[170:173], v[202:205], v[100:103]
	v_mfma_f32_16x16x32_bf16 v[96:99], v[178:181], v[202:205], v[96:99]
	v_mfma_f32_16x16x32_bf16 v[84:87], v[170:173], v[210:213], v[84:87]
	v_mfma_f32_16x16x32_bf16 v[80:83], v[178:181], v[210:213], v[80:83]
	s_setprio 0
	s_barrier
	s_add_i32 s56, s57, s78
	v_lshl_add_u64 v[158:159], s[74:75], 0, v[160:161]
	s_mov_b32 m0, s56
	ds_read_b128 v[182:185], v167 offset:16384
	ds_read_b128 v[186:189], v167 offset:17408
	ds_read_b128 v[190:193], v167 offset:18432
	ds_read_b128 v[194:197], v167 offset:19456
	ds_read_b128 v[198:201], v167 offset:20480
	ds_read_b128 v[202:205], v167 offset:21504
	ds_read_b128 v[206:209], v167 offset:22528
	ds_read_b128 v[210:213], v167 offset:23552
	global_load_lds_dwordx4 v[158:159], off
	s_add_i32 m0, s56, 0x2000
	s_add_u32 s56, s74, 0x40000
	v_lshl_add_u64 v[162:163], s[74:75], 0, v[144:145]
	s_addc_u32 s57, s75, 0
	s_add_i32 s23, s23, s78
	global_load_lds_dwordx4 v[162:163], off
	v_lshl_add_u64 v[214:215], s[56:57], 0, v[160:161]
	s_mov_b32 m0, s23
	v_lshl_add_u64 v[216:217], s[76:77], 0, v[146:147]
	global_load_lds_dwordx4 v[214:215], off
	v_lshl_add_u64 v[214:215], s[56:57], 0, v[144:145]
	s_add_i32 m0, s23, 0x2000
	s_nop 0
	global_load_lds_dwordx4 v[214:215], off
	v_lshl_add_u64 v[214:215], s[76:77], 0, v[148:149]
	s_mov_b32 m0, s79
	s_nop 0
	global_load_lds_dwordx4 v[214:215], off
	s_mov_b32 m0, s80
	s_nop 0
	global_load_lds_dwordx4 v[216:217], off
	s_waitcnt vmcnt(8)
	s_waitcnt lgkmcnt(0)
	s_barrier
; #define PG8_STAGE(bufoff, gbase, voff) do { _Pragma("unroll") for (int _i = 0; _i < 2; ++_i) \
;         __builtin_amdgcn_global_load_lds((const unsigned*)((const char*)(gbase) + (voff)[_i]), (PG8_LAS unsigned*)(lds + (bufoff) + ldsw + _i * 8192), 16, 0, 0); } while (0)
; #define PG8_LDA(dst, b, h) do { _Pragma("unroll") for (int m = 0; m < 4; ++m) _Pragma("unroll") for (int k = 0; k < 2; ++k) dst[m][k] = *(const PG8_LAS bf16x8*)(lds + PG8_SA(b, h) + aoff + m * 2048 + k * 1024); } while (0)
; #define PG8_LDB(dst, b, h) do { _Pragma("unroll") for (int n = 0; n < 2; ++n) _Pragma("unroll") for (int k = 0; k < 2; ++k) dst[n][k] = *(const PG8_LAS bf16x8*)(lds + PG8_SB(b, h) + boff + n * 2048 + k * 1024); } while (0)
; #define PG8_MMA(ai, bj, At, Bt) do { __builtin_amdgcn_s_setprio(1); _Pragma("unroll") for (int m = 0; m < 4; ++m) _Pragma("unroll") for (int n = 0; n < 2; ++n) _Pragma("unroll") for (int k = 0; k < 2; ++k) \
;         acc[ai][bj][m][n] = __builtin_amdgcn_mfma_f32_16x16x32_bf16(Bt[n][k], At[m][k], acc[ai][bj][m][n], 0, 0, 0); __builtin_amdgcn_s_setprio(0); } while (0)
; #define PG8_WAIT_V(n) asm volatile("s_waitcnt vmcnt(" #n ")" ::: "memory")
; #define PG8_WAIT_L(n) asm volatile("s_waitcnt lgkmcnt(" #n ")" ::: "memory")
; #define PG8_BAR __builtin_amdgcn_s_barrier()
; #define PG8_SCHED __builtin_amdgcn_sched_barrier(0)
; template <class Epi, class Sched, bool ALIGN_EPI = false, bool SP2 = false>
; __device__ __forceinline__ void gemm_phase(PG8_LAS unsigned char* lds, const Gemm g, const Sched& S, const Epi& E) {
;     ...
;             PG8_WAIT_V(8); PG8_WAIT_L(0); PG8_BAR; PG8_MMA(1, 0, At, B0); PG8_MMA(1, 1, At, B1); PG8_BAR; PG8_SCHED;
;             PG8_LDB(B0, 1, 0); PG8_LDB(B1, 1, 1); PG8_SCHED; PG8_LDA(At, 1, 0); PG8_STAGE(PG8_SA(0, 1), a2 + hstep, voffA);
;             PG8_WAIT_V(8); PG8_WAIT_L(0); PG8_BAR; PG8_MMA(0, 0, At, B0); PG8_MMA(0, 1, At, B1); PG8_BAR; PG8_SCHED;
	s_setprio 1
	v_mfma_f32_16x16x32_bf16 v[76:79], v[48:51], v[182:185], v[76:79]
	v_mfma_f32_16x16x32_bf16 v[72:75], v[56:59], v[182:185], v[72:75]
	v_mfma_f32_16x16x32_bf16 v[44:47], v[48:51], v[190:193], v[44:47]
	v_mfma_f32_16x16x32_bf16 v[40:43], v[56:59], v[190:193], v[40:43]
	v_mfma_f32_16x16x32_bf16 v[28:31], v[48:51], v[198:201], v[28:31]
	v_mfma_f32_16x16x32_bf16 v[24:27], v[56:59], v[198:201], v[24:27]
	v_mfma_f32_16x16x32_bf16 v[12:15], v[48:51], v[206:209], v[12:15]
	v_mfma_f32_16x16x32_bf16 v[8:11], v[56:59], v[206:209], v[8:11]
	v_mfma_f32_16x16x32_bf16 v[76:79], v[52:55], v[186:189], v[76:79]
	v_mfma_f32_16x16x32_bf16 v[72:75], v[60:63], v[186:189], v[72:75]
	v_mfma_f32_16x16x32_bf16 v[44:47], v[52:55], v[194:197], v[44:47]
	v_mfma_f32_16x16x32_bf16 v[40:43], v[60:63], v[194:197], v[40:43]
	v_mfma_f32_16x16x32_bf16 v[28:31], v[52:55], v[202:205], v[28:31]
	v_mfma_f32_16x16x32_bf16 v[24:27], v[60:63], v[202:205], v[24:27]
	v_mfma_f32_16x16x32_bf16 v[12:15], v[52:55], v[210:213], v[12:15]
	v_mfma_f32_16x16x32_bf16 v[8:11], v[60:63], v[210:213], v[8:11]
	s_setprio 0
	s_setprio 1
	v_mfma_f32_16x16x32_bf16 v[36:39], v[154:157], v[190:193], v[36:39]
	v_mfma_f32_16x16x32_bf16 v[32:35], v[174:177], v[190:193], v[32:35]
	v_mfma_f32_16x16x32_bf16 v[20:23], v[154:157], v[198:201], v[20:23]
	v_mfma_f32_16x16x32_bf16 v[16:19], v[174:177], v[198:201], v[16:19]
	v_mfma_f32_16x16x32_bf16 v[4:7], v[154:157], v[206:209], v[4:7]
	v_mfma_f32_16x16x32_bf16 v[0:3], v[174:177], v[206:209], v[0:3]
	v_mfma_f32_16x16x32_bf16 v[48:51], v[154:157], v[182:185], v[68:71]
	v_mfma_f32_16x16x32_bf16 v[52:55], v[174:177], v[182:185], v[64:67]
	v_mfma_f32_16x16x32_bf16 v[36:39], v[170:173], v[194:197], v[36:39]
	v_mfma_f32_16x16x32_bf16 v[32:35], v[178:181], v[194:197], v[32:35]
	v_mfma_f32_16x16x32_bf16 v[20:23], v[170:173], v[202:205], v[20:23]
	v_mfma_f32_16x16x32_bf16 v[16:19], v[178:181], v[202:205], v[16:19]
	v_mfma_f32_16x16x32_bf16 v[4:7], v[170:173], v[210:213], v[4:7]
	v_mfma_f32_16x16x32_bf16 v[0:3], v[178:181], v[210:213], v[0:3]
	v_mfma_f32_16x16x32_bf16 v[48:51], v[170:173], v[186:189], v[48:51]
	v_mfma_f32_16x16x32_bf16 v[52:55], v[178:181], v[186:189], v[52:55]
	s_setprio 0
	s_barrier
	s_add_i32 s23, 0, 0x18000
	s_add_i32 s58, 0, 0x1c000
	v_add_u32_e32 v68, s23, v165
	v_add_u32_e32 v169, s58, v165
	ds_read_b128 v[56:59], v68
	ds_read_b128 v[60:63], v68 offset:1024
	ds_read_b128 v[64:67], v68 offset:2048
	ds_read_b128 v[68:71], v68 offset:3072
	ds_read_b128 v[154:157], v169
	ds_read_b128 v[170:173], v169 offset:1024
	ds_read_b128 v[174:177], v169 offset:2048
	ds_read_b128 v[178:181], v169 offset:3072
	s_add_u32 s56, s76, 0x40000
	s_addc_u32 s57, s77, 0
	s_mov_b32 m0, s81
	v_lshl_add_u64 v[222:223], s[56:57], 0, v[148:149]
	ds_read_b128 v[182:185], v167 offset:32768
	ds_read_b128 v[186:189], v167 offset:33792
	ds_read_b128 v[190:193], v167 offset:34816
	ds_read_b128 v[194:197], v167 offset:35840
	ds_read_b128 v[198:201], v167 offset:36864
	ds_read_b128 v[202:205], v167 offset:37888
	ds_read_b128 v[206:209], v167 offset:38912
	ds_read_b128 v[210:213], v167 offset:39936
	global_load_lds_dwordx4 v[222:223], off
	v_lshl_add_u64 v[222:223], s[56:57], 0, v[146:147]
	s_mov_b32 m0, s84
	s_nop 0
	global_load_lds_dwordx4 v[222:223], off
	s_waitcnt vmcnt(8)
	s_waitcnt lgkmcnt(0)
	s_barrier
	s_setprio 1
	v_mfma_f32_16x16x32_bf16 v[140:143], v[56:59], v[182:185], v[140:143]
	v_mfma_f32_16x16x32_bf16 v[136:139], v[64:67], v[182:185], v[136:139]
	v_mfma_f32_16x16x32_bf16 v[124:127], v[56:59], v[190:193], v[124:127]
	v_mfma_f32_16x16x32_bf16 v[120:123], v[64:67], v[190:193], v[120:123]
	v_mfma_f32_16x16x32_bf16 v[108:111], v[56:59], v[198:201], v[108:111]
	v_mfma_f32_16x16x32_bf16 v[104:107], v[64:67], v[198:201], v[104:107]
	v_mfma_f32_16x16x32_bf16 v[92:95], v[56:59], v[206:209], v[92:95]
	v_mfma_f32_16x16x32_bf16 v[88:91], v[64:67], v[206:209], v[88:91]
	v_mfma_f32_16x16x32_bf16 v[140:143], v[60:63], v[186:189], v[140:143]
	v_mfma_f32_16x16x32_bf16 v[136:139], v[68:71], v[186:189], v[136:139]
	v_mfma_f32_16x16x32_bf16 v[124:127], v[60:63], v[194:197], v[124:127]
	v_mfma_f32_16x16x32_bf16 v[120:123], v[68:71], v[194:197], v[120:123]
	v_mfma_f32_16x16x32_bf16 v[108:111], v[60:63], v[202:205], v[108:111]
	v_mfma_f32_16x16x32_bf16 v[104:107], v[68:71], v[202:205], v[104:107]
	v_mfma_f32_16x16x32_bf16 v[92:95], v[60:63], v[210:213], v[92:95]
	v_mfma_f32_16x16x32_bf16 v[88:91], v[68:71], v[210:213], v[88:91]
	s_setprio 0
	s_setprio 1
	v_mfma_f32_16x16x32_bf16 v[132:135], v[154:157], v[182:185], v[132:135]
	v_mfma_f32_16x16x32_bf16 v[128:131], v[174:177], v[182:185], v[128:131]
	v_mfma_f32_16x16x32_bf16 v[116:119], v[154:157], v[190:193], v[116:119]
	v_mfma_f32_16x16x32_bf16 v[112:115], v[174:177], v[190:193], v[112:115]
	v_mfma_f32_16x16x32_bf16 v[100:103], v[154:157], v[198:201], v[100:103]
	v_mfma_f32_16x16x32_bf16 v[96:99], v[174:177], v[198:201], v[96:99]
	v_mfma_f32_16x16x32_bf16 v[84:87], v[154:157], v[206:209], v[84:87]
	v_mfma_f32_16x16x32_bf16 v[80:83], v[174:177], v[206:209], v[80:83]
	v_mfma_f32_16x16x32_bf16 v[132:135], v[170:173], v[186:189], v[132:135]
	v_mfma_f32_16x16x32_bf16 v[128:131], v[178:181], v[186:189], v[128:131]
	v_mfma_f32_16x16x32_bf16 v[116:119], v[170:173], v[194:197], v[116:119]
	v_mfma_f32_16x16x32_bf16 v[112:115], v[178:181], v[194:197], v[112:115]
	v_mfma_f32_16x16x32_bf16 v[100:103], v[170:173], v[202:205], v[100:103]
	v_mfma_f32_16x16x32_bf16 v[96:99], v[178:181], v[202:205], v[96:99]
	v_mfma_f32_16x16x32_bf16 v[84:87], v[170:173], v[210:213], v[84:87]
	v_mfma_f32_16x16x32_bf16 v[80:83], v[178:181], v[210:213], v[80:83]
	s_setprio 0
	s_barrier
; #define PG8_STAGE(bufoff, gbase, voff) do { _Pragma("unroll") for (int _i = 0; _i < 2; ++_i) \
;         __builtin_amdgcn_global_load_lds((const unsigned*)((const char*)(gbase) + (voff)[_i]), (PG8_LAS unsigned*)(lds + (bufoff) + ldsw + _i * 8192), 16, 0, 0); } while (0)
; #define PG8_LDA(dst, b, h) do { _Pragma("unroll") for (int m = 0; m < 4; ++m) _Pragma("unroll") for (int k = 0; k < 2; ++k) dst[m][k] = *(const PG8_LAS bf16x8*)(lds + PG8_SA(b, h) + aoff + m * 2048 + k * 1024); } while (0)
; #define PG8_MMA(ai, bj, At, Bt) do { __builtin_amdgcn_s_setprio(1); _Pragma("unroll") for (int m = 0; m < 4; ++m) _Pragma("unroll") for (int n = 0; n < 2; ++n) _Pragma("unroll") for (int k = 0; k < 2; ++k) \
;         acc[ai][bj][m][n] = __builtin_amdgcn_mfma_f32_16x16x32_bf16(Bt[n][k], At[m][k], acc[ai][bj][m][n], 0, 0, 0); __builtin_amdgcn_s_setprio(0); } while (0)
; #define PG8_WAIT_V(n) asm volatile("s_waitcnt vmcnt(" #n ")" ::: "memory")
; #define PG8_WAIT_L(n) asm volatile("s_waitcnt lgkmcnt(" #n ")" ::: "memory")
; #define PG8_BAR __builtin_amdgcn_s_barrier()
; #define PG8_SCHED __builtin_amdgcn_sched_barrier(0)
; template <class Epi, class Sched, bool ALIGN_EPI = false, bool SP2 = false>
; __device__ __forceinline__ void gemm_phase(PG8_LAS unsigned char* lds, const Gemm g, const Sched& S, const Epi& E) {
;     ...
;             PG8_LDA(At, 1, 1); PG8_STAGE(PG8_SB(1, 0), b3, voffB); PG8_STAGE(PG8_SB(1, 1), b3 + hstep, voffB); PG8_STAGE(PG8_SA(1, 0), a3, voffA);
;             PG8_WAIT_V(8); PG8_WAIT_L(0); PG8_BAR; PG8_MMA(1, 0, At, B0); PG8_MMA(1, 1, At, B1); PG8_BAR; PG8_SCHED;
	s_add_i32 s23, s23, s78
	v_lshl_add_u64 v[158:159], v[158:159], 0, s[24:25]
	s_mov_b32 m0, s23
	ds_read_b128 v[182:185], v167 offset:49152
	ds_read_b128 v[186:189], v167 offset:50176
	ds_read_b128 v[190:193], v167 offset:51200
	ds_read_b128 v[194:197], v167 offset:52224
	ds_read_b128 v[198:201], v167 offset:53248
	ds_read_b128 v[202:205], v167 offset:54272
	ds_read_b128 v[206:209], v167 offset:55296
	ds_read_b128 v[210:213], v167 offset:56320
	global_load_lds_dwordx4 v[158:159], off
	s_add_i32 m0, s23, 0x2000
	s_add_u32 s56, s74, 0x40080
	v_lshl_add_u64 v[158:159], v[162:163], 0, s[24:25]
	s_addc_u32 s57, s75, 0
	s_add_i32 s23, s58, s78
	global_load_lds_dwordx4 v[158:159], off
	v_lshl_add_u64 v[158:159], s[56:57], 0, v[160:161]
	s_mov_b32 m0, s23
	s_nop 0
	global_load_lds_dwordx4 v[158:159], off
	v_lshl_add_u64 v[158:159], s[56:57], 0, v[144:145]
	s_add_i32 m0, s23, 0x2000
	s_nop 0
	global_load_lds_dwordx4 v[158:159], off
	v_lshl_add_u64 v[158:159], v[214:215], 0, s[24:25]
	s_mov_b32 m0, s87
	s_nop 0
	global_load_lds_dwordx4 v[158:159], off
	v_lshl_add_u64 v[158:159], v[216:217], 0, s[24:25]
	s_mov_b32 m0, s96
	s_nop 0
	global_load_lds_dwordx4 v[158:159], off
	s_waitcnt vmcnt(8)
	s_waitcnt lgkmcnt(0)
	s_barrier
	s_setprio 1
	v_mfma_f32_16x16x32_bf16 v[76:79], v[56:59], v[182:185], v[76:79]
	v_mfma_f32_16x16x32_bf16 v[72:75], v[64:67], v[182:185], v[72:75]
	v_mfma_f32_16x16x32_bf16 v[44:47], v[56:59], v[190:193], v[44:47]
	v_mfma_f32_16x16x32_bf16 v[40:43], v[64:67], v[190:193], v[40:43]
	v_mfma_f32_16x16x32_bf16 v[28:31], v[56:59], v[198:201], v[28:31]
	v_mfma_f32_16x16x32_bf16 v[24:27], v[64:67], v[198:201], v[24:27]
	v_mfma_f32_16x16x32_bf16 v[12:15], v[56:59], v[206:209], v[12:15]
	v_mfma_f32_16x16x32_bf16 v[8:11], v[64:67], v[206:209], v[8:11]
	v_mfma_f32_16x16x32_bf16 v[76:79], v[60:63], v[186:189], v[76:79]
	v_mfma_f32_16x16x32_bf16 v[72:75], v[68:71], v[186:189], v[72:75]
	v_mfma_f32_16x16x32_bf16 v[44:47], v[60:63], v[194:197], v[44:47]
	v_mfma_f32_16x16x32_bf16 v[40:43], v[68:71], v[194:197], v[40:43]
	v_mfma_f32_16x16x32_bf16 v[28:31], v[60:63], v[202:205], v[28:31]
	v_mfma_f32_16x16x32_bf16 v[24:27], v[68:71], v[202:205], v[24:27]
	v_mfma_f32_16x16x32_bf16 v[12:15], v[60:63], v[210:213], v[12:15]
	v_mfma_f32_16x16x32_bf16 v[8:11], v[68:71], v[210:213], v[8:11]
	s_setprio 0
	s_setprio 1
	v_mfma_f32_16x16x32_bf16 v[48:51], v[154:157], v[182:185], v[48:51]
	v_mfma_f32_16x16x32_bf16 v[68:71], v[170:173], v[186:189], v[48:51]
	v_mfma_f32_16x16x32_bf16 v[48:51], v[174:177], v[182:185], v[52:55]
	v_mfma_f32_16x16x32_bf16 v[36:39], v[154:157], v[190:193], v[36:39]
	v_mfma_f32_16x16x32_bf16 v[32:35], v[174:177], v[190:193], v[32:35]
	v_mfma_f32_16x16x32_bf16 v[20:23], v[154:157], v[198:201], v[20:23]
	v_mfma_f32_16x16x32_bf16 v[16:19], v[174:177], v[198:201], v[16:19]
	v_mfma_f32_16x16x32_bf16 v[4:7], v[154:157], v[206:209], v[4:7]
	v_mfma_f32_16x16x32_bf16 v[0:3], v[174:177], v[206:209], v[0:3]
	v_mfma_f32_16x16x32_bf16 v[64:67], v[178:181], v[186:189], v[48:51]
	v_mfma_f32_16x16x32_bf16 v[36:39], v[170:173], v[194:197], v[36:39]
	v_mfma_f32_16x16x32_bf16 v[32:35], v[178:181], v[194:197], v[32:35]
	v_mfma_f32_16x16x32_bf16 v[20:23], v[170:173], v[202:205], v[20:23]
	v_mfma_f32_16x16x32_bf16 v[16:19], v[178:181], v[202:205], v[16:19]
	v_mfma_f32_16x16x32_bf16 v[4:7], v[170:173], v[210:213], v[4:7]
	v_mfma_f32_16x16x32_bf16 v[0:3], v[178:181], v[210:213], v[0:3]
	s_setprio 0
	s_barrier
	s_add_i32 s22, s22, 2
	s_add_u32 s72, s72, 0x100
	s_addc_u32 s73, s73, 0
	s_add_u32 s50, s50, 0x100
	s_addc_u32 s51, s51, 0
	s_cmp_gt_u32 s22, 13
	s_cbranch_scc0 .LBB0_703
	s_and_b64 vcc, exec, s[12:13]
	s_cbranch_vccz .LBB0_706
	s_barrier

; #define PG8_STAGE(bufoff, gbase, voff) do { _Pragma("unroll") for (int _i = 0; _i < 2; ++_i) \
;         __builtin_amdgcn_global_load_lds((const unsigned*)((const char*)(gbase) + (voff)[_i]), (PG8_LAS unsigned*)(lds + (bufoff) + ldsw + _i * 8192), 16, 0, 0); } while (0)
; #define PG8_LDA(dst, b, h) do { _Pragma("unroll") for (int m = 0; m < 4; ++m) _Pragma("unroll") for (int k = 0; k < 2; ++k) dst[m][k] = *(const PG8_LAS bf16x8*)(lds + PG8_SA(b, h) + aoff + m * 2048 + k * 1024); } while (0)
; #define PG8_LDB(dst, b, h) do { _Pragma("unroll") for (int n = 0; n < 2; ++n) _Pragma("unroll") for (int k = 0; k < 2; ++k) dst[n][k] = *(const PG8_LAS bf16x8*)(lds + PG8_SB(b, h) + boff + n * 2048 + k * 1024); } while (0)
; #define PG8_MMA(ai, bj, At, Bt) do { __builtin_amdgcn_s_setprio(1); _Pragma("unroll") for (int m = 0; m < 4; ++m) _Pragma("unroll") for (int n = 0; n < 2; ++n) _Pragma("unroll") for (int k = 0; k < 2; ++k) \
;         acc[ai][bj][m][n] = __builtin_amdgcn_mfma_f32_16x16x32_bf16(Bt[n][k], At[m][k], acc[ai][bj][m][n], 0, 0, 0); __builtin_amdgcn_s_setprio(0); } while (0)
; #define PG8_WAIT_V(n) asm volatile("s_waitcnt vmcnt(" #n ")" ::: "memory")
; #define PG8_WAIT_L(n) asm volatile("s_waitcnt lgkmcnt(" #n ")" ::: "memory")
; template <class Epi, class Sched, bool ALIGN_EPI = false, bool SP2 = false>
; __device__ __forceinline__ void gemm_phase(PG8_LAS unsigned char* lds, const Gemm g, const Sched& S, const Epi& E) {
;     ...
;             const bool last = (t == nt - 2);
;             const char* a1 = cA + (size_t)(t + 1) * kstep;
;             const char* a2 = last ? nA : cA + (size_t)(t + 2) * kstep; const char* b2 = last ? nB : cB + (size_t)(t + 2) * kstep;
;             const char* a3 = a2 + kstep; const char* b3 = b2 + kstep;
;             if (last && has_next) S.a_ready(nxt);
;             if constexpr (SP2) {
;             PG8_LDB(B0, 0, 0); PG8_LDB(B1, 0, 1); PG8_SCHED; PG8_LDA(At, 0, 0); PG8_STAGE(PG8_SA(1, 1), a1 + hstep, voffA);
;             PG8_WAIT_V(8); PG8_WAIT_L(0); PG8_BAR; PG8_MMA(0, 0, At, B0); PG8_MMA(0, 1, At, B1); PG8_BAR; PG8_SCHED;
;             PG8_LDA(At, 0, 1); PG8_STAGE(PG8_SB(0, 0), b2, voffB); PG8_STAGE(PG8_SB(0, 1), b2 + hstep, voffB); PG8_STAGE(PG8_SA(0, 0), a2, voffA);
;             PG8_WAIT_V(8); PG8_WAIT_L(0); PG8_BAR; PG8_MMA(1, 0, At, B0); PG8_MMA(1, 1, At, B1); PG8_BAR; PG8_SCHED;
.LBB0_776:
	s_add_u32 s68, s66, 0x100
	s_addc_u32 s69, s67, 0
	s_add_i32 s58, 0, 0x10000
	s_cmp_eq_u32 s23, 40
	s_cselect_b32 s73, s9, s69
	s_cselect_b32 s72, s8, s68
	s_cselect_b32 s71, s65, s22
	s_cselect_b32 s70, s64, s57
	s_add_i32 s62, 0, 0x14000
	v_add_u32_e32 v100, s58, v155
	v_add_u32_e32 v158, s62, v155
	ds_read_b128 v[48:51], v100
	ds_read_b128 v[84:87], v100 offset:1024
	ds_read_b128 v[96:99], v100 offset:2048
	ds_read_b128 v[100:103], v100 offset:3072
	ds_read_b128 v[150:153], v158
	ds_read_b128 v[162:165], v158 offset:1024
	ds_read_b128 v[166:169], v158 offset:2048
	ds_read_b128 v[170:173], v158 offset:3072
	v_lshl_add_u64 v[158:159], s[66:67], 0, v[146:147]
	s_add_i32 m0, s4, 0xc000
	ds_read_b128 v[174:177], v157
	ds_read_b128 v[178:181], v157 offset:1024
	ds_read_b128 v[182:185], v157 offset:2048
	ds_read_b128 v[186:189], v157 offset:3072
	ds_read_b128 v[190:193], v157 offset:4096
	ds_read_b128 v[194:197], v157 offset:5120
	ds_read_b128 v[198:201], v157 offset:6144
	ds_read_b128 v[202:205], v157 offset:7168
	global_load_lds_dwordx4 v[158:159], off
	v_lshl_add_u64 v[158:159], s[66:67], 0, v[148:149]
	s_add_i32 m0, s4, 0xe000
	s_nop 0
	global_load_lds_dwordx4 v[158:159], off
	s_waitcnt vmcnt(8)
	s_waitcnt lgkmcnt(0)
	s_barrier
	s_setprio 1
	v_mfma_f32_16x16x32_bf16 v[140:143], v[48:51], v[174:177], v[140:143]
	v_mfma_f32_16x16x32_bf16 v[136:139], v[96:99], v[174:177], v[136:139]
	v_mfma_f32_16x16x32_bf16 v[124:127], v[48:51], v[182:185], v[124:127]
	v_mfma_f32_16x16x32_bf16 v[120:123], v[96:99], v[182:185], v[120:123]
	v_mfma_f32_16x16x32_bf16 v[108:111], v[48:51], v[190:193], v[108:111]
	v_mfma_f32_16x16x32_bf16 v[104:107], v[96:99], v[190:193], v[104:107]
	v_mfma_f32_16x16x32_bf16 v[80:83], v[48:51], v[198:201], v[80:83]
	v_mfma_f32_16x16x32_bf16 v[76:79], v[96:99], v[198:201], v[76:79]
	v_mfma_f32_16x16x32_bf16 v[140:143], v[84:87], v[178:181], v[140:143]
	v_mfma_f32_16x16x32_bf16 v[136:139], v[100:103], v[178:181], v[136:139]
	v_mfma_f32_16x16x32_bf16 v[124:127], v[84:87], v[186:189], v[124:127]
	v_mfma_f32_16x16x32_bf16 v[120:123], v[100:103], v[186:189], v[120:123]
	v_mfma_f32_16x16x32_bf16 v[108:111], v[84:87], v[194:197], v[108:111]
	v_mfma_f32_16x16x32_bf16 v[104:107], v[100:103], v[194:197], v[104:107]
	v_mfma_f32_16x16x32_bf16 v[80:83], v[84:87], v[202:205], v[80:83]
	v_mfma_f32_16x16x32_bf16 v[76:79], v[100:103], v[202:205], v[76:79]
	s_setprio 0
	s_setprio 1
	v_mfma_f32_16x16x32_bf16 v[132:135], v[150:153], v[174:177], v[132:135]
	v_mfma_f32_16x16x32_bf16 v[128:131], v[166:169], v[174:177], v[128:131]
	v_mfma_f32_16x16x32_bf16 v[116:119], v[150:153], v[182:185], v[116:119]
	v_mfma_f32_16x16x32_bf16 v[112:115], v[166:169], v[182:185], v[112:115]
	v_mfma_f32_16x16x32_bf16 v[92:95], v[150:153], v[190:193], v[92:95]
	v_mfma_f32_16x16x32_bf16 v[88:91], v[166:169], v[190:193], v[88:91]
	v_mfma_f32_16x16x32_bf16 v[72:75], v[150:153], v[198:201], v[72:75]
	v_mfma_f32_16x16x32_bf16 v[68:71], v[166:169], v[198:201], v[68:71]
	v_mfma_f32_16x16x32_bf16 v[132:135], v[162:165], v[178:181], v[132:135]
	v_mfma_f32_16x16x32_bf16 v[128:131], v[170:173], v[178:181], v[128:131]
	v_mfma_f32_16x16x32_bf16 v[116:119], v[162:165], v[186:189], v[116:119]
	v_mfma_f32_16x16x32_bf16 v[112:115], v[170:173], v[186:189], v[112:115]
	v_mfma_f32_16x16x32_bf16 v[92:95], v[162:165], v[194:197], v[92:95]
	v_mfma_f32_16x16x32_bf16 v[88:91], v[170:173], v[194:197], v[88:91]
	v_mfma_f32_16x16x32_bf16 v[72:75], v[162:165], v[202:205], v[72:75]
	v_mfma_f32_16x16x32_bf16 v[68:71], v[170:173], v[202:205], v[68:71]
	s_setprio 0
	s_barrier
	s_add_i32 s58, s58, s3
	v_lshl_add_u64 v[158:159], s[70:71], 0, v[160:161]
	s_mov_b32 m0, s58
	ds_read_b128 v[174:177], v157 offset:16384
	ds_read_b128 v[178:181], v157 offset:17408
	ds_read_b128 v[182:185], v157 offset:18432
	ds_read_b128 v[186:189], v157 offset:19456
	ds_read_b128 v[190:193], v157 offset:20480
	ds_read_b128 v[194:197], v157 offset:21504
	ds_read_b128 v[198:201], v157 offset:22528
	ds_read_b128 v[202:205], v157 offset:23552
	global_load_lds_dwordx4 v[158:159], off
	s_add_i32 m0, s58, 0x2000
	s_add_u32 s58, s70, 0xb0000
	v_lshl_add_u64 v[206:207], s[70:71], 0, v[144:145]
	s_addc_u32 s59, s71, 0
	s_add_i32 s62, s62, s3
	global_load_lds_dwordx4 v[206:207], off
	v_lshl_add_u64 v[208:209], s[58:59], 0, v[160:161]
	s_mov_b32 m0, s62
	v_lshl_add_u64 v[210:211], s[72:73], 0, v[144:145]
	global_load_lds_dwordx4 v[208:209], off
	v_lshl_add_u64 v[208:209], s[58:59], 0, v[144:145]
	s_add_i32 m0, s62, 0x2000
	s_nop 0
	global_load_lds_dwordx4 v[208:209], off
	v_lshl_add_u64 v[208:209], s[72:73], 0, v[160:161]
	s_mov_b32 m0, s4
	s_nop 0
	global_load_lds_dwordx4 v[208:209], off
	s_mov_b32 m0, s5
	s_nop 0
	global_load_lds_dwordx4 v[210:211], off
	s_waitcnt vmcnt(8)
	s_waitcnt lgkmcnt(0)
	s_barrier
; #define PG8_STAGE(bufoff, gbase, voff) do { _Pragma("unroll") for (int _i = 0; _i < 2; ++_i) \
;         __builtin_amdgcn_global_load_lds((const unsigned*)((const char*)(gbase) + (voff)[_i]), (PG8_LAS unsigned*)(lds + (bufoff) + ldsw + _i * 8192), 16, 0, 0); } while (0)
; #define PG8_LDA(dst, b, h) do { _Pragma("unroll") for (int m = 0; m < 4; ++m) _Pragma("unroll") for (int k = 0; k < 2; ++k) dst[m][k] = *(const PG8_LAS bf16x8*)(lds + PG8_SA(b, h) + aoff + m * 2048 + k * 1024); } while (0)
; #define PG8_LDB(dst, b, h) do { _Pragma("unroll") for (int n = 0; n < 2; ++n) _Pragma("unroll") for (int k = 0; k < 2; ++k) dst[n][k] = *(const PG8_LAS bf16x8*)(lds + PG8_SB(b, h) + boff + n * 2048 + k * 1024); } while (0)
; #define PG8_MMA(ai, bj, At, Bt) do { __builtin_amdgcn_s_setprio(1); _Pragma("unroll") for (int m = 0; m < 4; ++m) _Pragma("unroll") for (int n = 0; n < 2; ++n) _Pragma("unroll") for (int k = 0; k < 2; ++k) \
;         acc[ai][bj][m][n] = __builtin_amdgcn_mfma_f32_16x16x32_bf16(Bt[n][k], At[m][k], acc[ai][bj][m][n], 0, 0, 0); __builtin_amdgcn_s_setprio(0); } while (0)
; #define PG8_WAIT_V(n) asm volatile("s_waitcnt vmcnt(" #n ")" ::: "memory")
; #define PG8_WAIT_L(n) asm volatile("s_waitcnt lgkmcnt(" #n ")" ::: "memory")
; #define PG8_BAR __builtin_amdgcn_s_barrier()
; #define PG8_SCHED __builtin_amdgcn_sched_barrier(0)
; template <class Epi, class Sched, bool ALIGN_EPI = false, bool SP2 = false>
; __device__ __forceinline__ void gemm_phase(PG8_LAS unsigned char* lds, const Gemm g, const Sched& S, const Epi& E) {
;     ...
;             PG8_WAIT_V(8); PG8_WAIT_L(0); PG8_BAR; PG8_MMA(1, 0, At, B0); PG8_MMA(1, 1, At, B1); PG8_BAR; PG8_SCHED;
;             PG8_LDB(B0, 1, 0); PG8_LDB(B1, 1, 1); PG8_SCHED; PG8_LDA(At, 1, 0); PG8_STAGE(PG8_SA(0, 1), a2 + hstep, voffA);
;             PG8_WAIT_V(8); PG8_WAIT_L(0); PG8_BAR; PG8_MMA(0, 0, At, B0); PG8_MMA(0, 1, At, B1); PG8_BAR; PG8_SCHED;
	s_setprio 1
	v_mfma_f32_16x16x32_bf16 v[64:67], v[48:51], v[174:177], v[64:67]
	v_mfma_f32_16x16x32_bf16 v[60:63], v[96:99], v[174:177], v[60:63]
	v_mfma_f32_16x16x32_bf16 v[44:47], v[48:51], v[182:185], v[44:47]
	v_mfma_f32_16x16x32_bf16 v[40:43], v[96:99], v[182:185], v[40:43]
	v_mfma_f32_16x16x32_bf16 v[28:31], v[48:51], v[190:193], v[28:31]
	v_mfma_f32_16x16x32_bf16 v[24:27], v[96:99], v[190:193], v[24:27]
	v_mfma_f32_16x16x32_bf16 v[12:15], v[48:51], v[198:201], v[12:15]
	v_mfma_f32_16x16x32_bf16 v[8:11], v[96:99], v[198:201], v[8:11]
	v_mfma_f32_16x16x32_bf16 v[64:67], v[84:87], v[178:181], v[64:67]
	v_mfma_f32_16x16x32_bf16 v[60:63], v[100:103], v[178:181], v[60:63]
	v_mfma_f32_16x16x32_bf16 v[44:47], v[84:87], v[186:189], v[44:47]
	v_mfma_f32_16x16x32_bf16 v[40:43], v[100:103], v[186:189], v[40:43]
	v_mfma_f32_16x16x32_bf16 v[28:31], v[84:87], v[194:197], v[28:31]
	v_mfma_f32_16x16x32_bf16 v[24:27], v[100:103], v[194:197], v[24:27]
	v_mfma_f32_16x16x32_bf16 v[12:15], v[84:87], v[202:205], v[12:15]
	v_mfma_f32_16x16x32_bf16 v[8:11], v[100:103], v[202:205], v[8:11]
	s_setprio 0
	s_setprio 1
	v_mfma_f32_16x16x32_bf16 v[52:55], v[166:169], v[174:177], v[52:55]
	v_mfma_f32_16x16x32_bf16 v[36:39], v[150:153], v[182:185], v[36:39]
	v_mfma_f32_16x16x32_bf16 v[32:35], v[166:169], v[182:185], v[32:35]
	v_mfma_f32_16x16x32_bf16 v[20:23], v[150:153], v[190:193], v[20:23]
	v_mfma_f32_16x16x32_bf16 v[16:19], v[166:169], v[190:193], v[16:19]
	v_mfma_f32_16x16x32_bf16 v[4:7], v[150:153], v[198:201], v[4:7]
	v_mfma_f32_16x16x32_bf16 v[0:3], v[166:169], v[198:201], v[0:3]
	v_mfma_f32_16x16x32_bf16 v[48:51], v[150:153], v[174:177], v[56:59]
	v_mfma_f32_16x16x32_bf16 v[52:55], v[170:173], v[178:181], v[52:55]
	v_mfma_f32_16x16x32_bf16 v[36:39], v[162:165], v[186:189], v[36:39]
	v_mfma_f32_16x16x32_bf16 v[32:35], v[170:173], v[186:189], v[32:35]
	v_mfma_f32_16x16x32_bf16 v[20:23], v[162:165], v[194:197], v[20:23]
	v_mfma_f32_16x16x32_bf16 v[16:19], v[170:173], v[194:197], v[16:19]
	v_mfma_f32_16x16x32_bf16 v[4:7], v[162:165], v[202:205], v[4:7]
	v_mfma_f32_16x16x32_bf16 v[0:3], v[170:173], v[202:205], v[0:3]
	v_mfma_f32_16x16x32_bf16 v[48:51], v[162:165], v[178:181], v[48:51]
	s_setprio 0
	s_barrier
	s_add_i32 s62, 0, 0x18000
	s_add_i32 s63, 0, 0x1c000
	v_add_u32_e32 v100, s62, v155
	v_add_u32_e32 v170, s63, v155
	ds_read_b128 v[56:59], v100
	ds_read_b128 v[84:87], v100 offset:1024
	ds_read_b128 v[96:99], v100 offset:2048
	ds_read_b128 v[100:103], v100 offset:3072
	ds_read_b128 v[150:153], v170
	ds_read_b128 v[162:165], v170 offset:1024
	ds_read_b128 v[166:169], v170 offset:2048
	ds_read_b128 v[170:173], v170 offset:3072
	s_add_u32 s58, s72, 0xb0000
	s_addc_u32 s59, s73, 0
	s_mov_b32 m0, s28
	v_lshl_add_u64 v[212:213], s[58:59], 0, v[160:161]
	ds_read_b128 v[174:177], v157 offset:32768
	ds_read_b128 v[178:181], v157 offset:33792
	ds_read_b128 v[182:185], v157 offset:34816
	ds_read_b128 v[186:189], v157 offset:35840
	ds_read_b128 v[190:193], v157 offset:36864
	ds_read_b128 v[194:197], v157 offset:37888
	ds_read_b128 v[198:201], v157 offset:38912
	ds_read_b128 v[202:205], v157 offset:39936
	global_load_lds_dwordx4 v[212:213], off
	v_lshl_add_u64 v[212:213], s[58:59], 0, v[144:145]
	s_mov_b32 m0, s29
	s_nop 0
	global_load_lds_dwordx4 v[212:213], off
	s_waitcnt vmcnt(8)
	s_waitcnt lgkmcnt(0)
	s_barrier
	s_setprio 1
	v_mfma_f32_16x16x32_bf16 v[140:143], v[56:59], v[174:177], v[140:143]
	v_mfma_f32_16x16x32_bf16 v[136:139], v[96:99], v[174:177], v[136:139]
	v_mfma_f32_16x16x32_bf16 v[124:127], v[56:59], v[182:185], v[124:127]
	v_mfma_f32_16x16x32_bf16 v[120:123], v[96:99], v[182:185], v[120:123]
	v_mfma_f32_16x16x32_bf16 v[108:111], v[56:59], v[190:193], v[108:111]
	v_mfma_f32_16x16x32_bf16 v[104:107], v[96:99], v[190:193], v[104:107]
	v_mfma_f32_16x16x32_bf16 v[80:83], v[56:59], v[198:201], v[80:83]
	v_mfma_f32_16x16x32_bf16 v[76:79], v[96:99], v[198:201], v[76:79]
	v_mfma_f32_16x16x32_bf16 v[140:143], v[84:87], v[178:181], v[140:143]
	v_mfma_f32_16x16x32_bf16 v[136:139], v[100:103], v[178:181], v[136:139]
	v_mfma_f32_16x16x32_bf16 v[124:127], v[84:87], v[186:189], v[124:127]
	v_mfma_f32_16x16x32_bf16 v[120:123], v[100:103], v[186:189], v[120:123]
	v_mfma_f32_16x16x32_bf16 v[108:111], v[84:87], v[194:197], v[108:111]
	v_mfma_f32_16x16x32_bf16 v[104:107], v[100:103], v[194:197], v[104:107]
	v_mfma_f32_16x16x32_bf16 v[80:83], v[84:87], v[202:205], v[80:83]
	v_mfma_f32_16x16x32_bf16 v[76:79], v[100:103], v[202:205], v[76:79]
	s_setprio 0
	s_setprio 1
	v_mfma_f32_16x16x32_bf16 v[132:135], v[150:153], v[174:177], v[132:135]
	v_mfma_f32_16x16x32_bf16 v[128:131], v[166:169], v[174:177], v[128:131]
	v_mfma_f32_16x16x32_bf16 v[116:119], v[150:153], v[182:185], v[116:119]
	v_mfma_f32_16x16x32_bf16 v[112:115], v[166:169], v[182:185], v[112:115]
	v_mfma_f32_16x16x32_bf16 v[92:95], v[150:153], v[190:193], v[92:95]
	v_mfma_f32_16x16x32_bf16 v[88:91], v[166:169], v[190:193], v[88:91]
	v_mfma_f32_16x16x32_bf16 v[72:75], v[150:153], v[198:201], v[72:75]
	v_mfma_f32_16x16x32_bf16 v[68:71], v[166:169], v[198:201], v[68:71]
	v_mfma_f32_16x16x32_bf16 v[132:135], v[162:165], v[178:181], v[132:135]
	v_mfma_f32_16x16x32_bf16 v[128:131], v[170:173], v[178:181], v[128:131]
	v_mfma_f32_16x16x32_bf16 v[116:119], v[162:165], v[186:189], v[116:119]
	v_mfma_f32_16x16x32_bf16 v[112:115], v[170:173], v[186:189], v[112:115]
	v_mfma_f32_16x16x32_bf16 v[92:95], v[162:165], v[194:197], v[92:95]
	v_mfma_f32_16x16x32_bf16 v[88:91], v[170:173], v[194:197], v[88:91]
	v_mfma_f32_16x16x32_bf16 v[72:75], v[162:165], v[202:205], v[72:75]
	v_mfma_f32_16x16x32_bf16 v[68:71], v[170:173], v[202:205], v[68:71]
	s_setprio 0
	s_barrier
; #define PG8_STAGE(bufoff, gbase, voff) do { _Pragma("unroll") for (int _i = 0; _i < 2; ++_i) \
;         __builtin_amdgcn_global_load_lds((const unsigned*)((const char*)(gbase) + (voff)[_i]), (PG8_LAS unsigned*)(lds + (bufoff) + ldsw + _i * 8192), 16, 0, 0); } while (0)
; #define PG8_LDA(dst, b, h) do { _Pragma("unroll") for (int m = 0; m < 4; ++m) _Pragma("unroll") for (int k = 0; k < 2; ++k) dst[m][k] = *(const PG8_LAS bf16x8*)(lds + PG8_SA(b, h) + aoff + m * 2048 + k * 1024); } while (0)
; #define PG8_MMA(ai, bj, At, Bt) do { __builtin_amdgcn_s_setprio(1); _Pragma("unroll") for (int m = 0; m < 4; ++m) _Pragma("unroll") for (int n = 0; n < 2; ++n) _Pragma("unroll") for (int k = 0; k < 2; ++k) \
;         acc[ai][bj][m][n] = __builtin_amdgcn_mfma_f32_16x16x32_bf16(Bt[n][k], At[m][k], acc[ai][bj][m][n], 0, 0, 0); __builtin_amdgcn_s_setprio(0); } while (0)
; #define PG8_WAIT_V(n) asm volatile("s_waitcnt vmcnt(" #n ")" ::: "memory")
; #define PG8_WAIT_L(n) asm volatile("s_waitcnt lgkmcnt(" #n ")" ::: "memory")
; #define PG8_BAR __builtin_amdgcn_s_barrier()
; #define PG8_SCHED __builtin_amdgcn_sched_barrier(0)
; template <class Epi, class Sched, bool ALIGN_EPI = false, bool SP2 = false>
; __device__ __forceinline__ void gemm_phase(PG8_LAS unsigned char* lds, const Gemm g, const Sched& S, const Epi& E) {
;     ...
;             PG8_LDA(At, 1, 1); PG8_STAGE(PG8_SB(1, 0), b3, voffB); PG8_STAGE(PG8_SB(1, 1), b3 + hstep, voffB); PG8_STAGE(PG8_SA(1, 0), a3, voffA);
;             PG8_WAIT_V(8); PG8_WAIT_L(0); PG8_BAR; PG8_MMA(1, 0, At, B0); PG8_MMA(1, 1, At, B1); PG8_BAR; PG8_SCHED;
	s_add_i32 s58, s62, s3
	v_lshl_add_u64 v[158:159], v[158:159], 0, s[24:25]
	s_mov_b32 m0, s58
	ds_read_b128 v[174:177], v157 offset:49152
	ds_read_b128 v[178:181], v157 offset:50176
	ds_read_b128 v[182:185], v157 offset:51200
	ds_read_b128 v[186:189], v157 offset:52224
	ds_read_b128 v[190:193], v157 offset:53248
	ds_read_b128 v[194:197], v157 offset:54272
	ds_read_b128 v[198:201], v157 offset:55296
	ds_read_b128 v[202:205], v157 offset:56320
	global_load_lds_dwordx4 v[158:159], off
	s_add_i32 m0, s58, 0x2000
	s_add_u32 s58, s70, 0xb0080
	v_lshl_add_u64 v[158:159], v[206:207], 0, s[24:25]
	s_addc_u32 s59, s71, 0
	s_add_i32 s62, s63, s3
	global_load_lds_dwordx4 v[158:159], off
	v_lshl_add_u64 v[158:159], s[58:59], 0, v[160:161]
	s_mov_b32 m0, s62
	s_nop 0
	global_load_lds_dwordx4 v[158:159], off
	v_lshl_add_u64 v[158:159], s[58:59], 0, v[144:145]
	s_add_i32 m0, s62, 0x2000
	s_nop 0
	global_load_lds_dwordx4 v[158:159], off
	v_lshl_add_u64 v[158:159], v[208:209], 0, s[24:25]
	s_mov_b32 m0, s34
	s_nop 0
	global_load_lds_dwordx4 v[158:159], off
	v_lshl_add_u64 v[158:159], v[210:211], 0, s[24:25]
	s_mov_b32 m0, s35
	s_nop 0
	global_load_lds_dwordx4 v[158:159], off
	s_waitcnt vmcnt(8)
	s_waitcnt lgkmcnt(0)
	s_barrier
	s_setprio 1
	v_mfma_f32_16x16x32_bf16 v[64:67], v[56:59], v[174:177], v[64:67]
	v_mfma_f32_16x16x32_bf16 v[60:63], v[96:99], v[174:177], v[60:63]
	v_mfma_f32_16x16x32_bf16 v[44:47], v[56:59], v[182:185], v[44:47]
	v_mfma_f32_16x16x32_bf16 v[40:43], v[96:99], v[182:185], v[40:43]
	v_mfma_f32_16x16x32_bf16 v[28:31], v[56:59], v[190:193], v[28:31]
	v_mfma_f32_16x16x32_bf16 v[24:27], v[96:99], v[190:193], v[24:27]
	v_mfma_f32_16x16x32_bf16 v[12:15], v[56:59], v[198:201], v[12:15]
	v_mfma_f32_16x16x32_bf16 v[8:11], v[96:99], v[198:201], v[8:11]
	v_mfma_f32_16x16x32_bf16 v[64:67], v[84:87], v[178:181], v[64:67]
	v_mfma_f32_16x16x32_bf16 v[60:63], v[100:103], v[178:181], v[60:63]
	v_mfma_f32_16x16x32_bf16 v[44:47], v[84:87], v[186:189], v[44:47]
	v_mfma_f32_16x16x32_bf16 v[40:43], v[100:103], v[186:189], v[40:43]
	v_mfma_f32_16x16x32_bf16 v[28:31], v[84:87], v[194:197], v[28:31]
	v_mfma_f32_16x16x32_bf16 v[24:27], v[100:103], v[194:197], v[24:27]
	v_mfma_f32_16x16x32_bf16 v[12:15], v[84:87], v[202:205], v[12:15]
	v_mfma_f32_16x16x32_bf16 v[8:11], v[100:103], v[202:205], v[8:11]
	s_setprio 0
	s_setprio 1
	v_mfma_f32_16x16x32_bf16 v[48:51], v[150:153], v[174:177], v[48:51]
	v_mfma_f32_16x16x32_bf16 v[56:59], v[162:165], v[178:181], v[48:51]
	v_mfma_f32_16x16x32_bf16 v[48:51], v[166:169], v[174:177], v[52:55]
	v_mfma_f32_16x16x32_bf16 v[36:39], v[150:153], v[182:185], v[36:39]
	v_mfma_f32_16x16x32_bf16 v[32:35], v[166:169], v[182:185], v[32:35]
	v_mfma_f32_16x16x32_bf16 v[20:23], v[150:153], v[190:193], v[20:23]
	v_mfma_f32_16x16x32_bf16 v[16:19], v[166:169], v[190:193], v[16:19]
	v_mfma_f32_16x16x32_bf16 v[4:7], v[150:153], v[198:201], v[4:7]
	v_mfma_f32_16x16x32_bf16 v[0:3], v[166:169], v[198:201], v[0:3]
	v_mfma_f32_16x16x32_bf16 v[52:55], v[170:173], v[178:181], v[48:51]
	v_mfma_f32_16x16x32_bf16 v[36:39], v[162:165], v[186:189], v[36:39]
	v_mfma_f32_16x16x32_bf16 v[32:35], v[170:173], v[186:189], v[32:35]
	v_mfma_f32_16x16x32_bf16 v[20:23], v[162:165], v[194:197], v[20:23]
	v_mfma_f32_16x16x32_bf16 v[16:19], v[170:173], v[194:197], v[16:19]
	v_mfma_f32_16x16x32_bf16 v[4:7], v[162:165], v[202:205], v[4:7]
	v_mfma_f32_16x16x32_bf16 v[0:3], v[170:173], v[202:205], v[0:3]
	s_setprio 0
	s_barrier
	s_add_i32 s23, s23, 2
	s_add_u32 s57, s57, 0x100
	s_addc_u32 s22, s22, 0
	s_cmp_gt_u32 s23, 41
	s_mov_b64 s[66:67], s[68:69]
	s_cbranch_scc0 .LBB0_776
	s_and_b64 vcc, exec, s[12:13]
	s_cbranch_vccz .LBB0_779
	s_barrier

; #define PG8_STAGE(bufoff, gbase, voff) do { _Pragma("unroll") for (int _i = 0; _i < 2; ++_i) \
;         __builtin_amdgcn_global_load_lds((const unsigned*)((const char*)(gbase) + (voff)[_i]), (PG8_LAS unsigned*)(lds + (bufoff) + ldsw + _i * 8192), 16, 0, 0); } while (0)
; #define PG8_LDA(dst, b, h) do { _Pragma("unroll") for (int m = 0; m < 4; ++m) _Pragma("unroll") for (int k = 0; k < 2; ++k) dst[m][k] = *(const PG8_LAS bf16x8*)(lds + PG8_SA(b, h) + aoff + m * 2048 + k * 1024); } while (0)
; #define PG8_LDB(dst, b, h) do { _Pragma("unroll") for (int n = 0; n < 2; ++n) _Pragma("unroll") for (int k = 0; k < 2; ++k) dst[n][k] = *(const PG8_LAS bf16x8*)(lds + PG8_SB(b, h) + boff + n * 2048 + k * 1024); } while (0)
; #define PG8_MMA(ai, bj, At, Bt) do { __builtin_amdgcn_s_setprio(1); _Pragma("unroll") for (int m = 0; m < 4; ++m) _Pragma("unroll") for (int n = 0; n < 2; ++n) _Pragma("unroll") for (int k = 0; k < 2; ++k) \
;         acc[ai][bj][m][n] = __builtin_amdgcn_mfma_f32_16x16x32_bf16(Bt[n][k], At[m][k], acc[ai][bj][m][n], 0, 0, 0); __builtin_amdgcn_s_setprio(0); } while (0)
; #define PG8_WAIT_V(n) asm volatile("s_waitcnt vmcnt(" #n ")" ::: "memory")
; #define PG8_WAIT_L(n) asm volatile("s_waitcnt lgkmcnt(" #n ")" ::: "memory")
; template <class Epi, class Sched, bool ALIGN_EPI = false, bool SP2 = false>
; __device__ __forceinline__ void gemm_phase(PG8_LAS unsigned char* lds, const Gemm g, const Sched& S, const Epi& E) {
;     ...
;             const bool last = (t == nt - 2);
;             const char* a1 = cA + (size_t)(t + 1) * kstep;
;             const char* a2 = last ? nA : cA + (size_t)(t + 2) * kstep; const char* b2 = last ? nB : cB + (size_t)(t + 2) * kstep;
;             const char* a3 = a2 + kstep; const char* b3 = b2 + kstep;
;             if (last && has_next) S.a_ready(nxt);
;             if constexpr (SP2) {
;             PG8_LDB(B0, 0, 0); PG8_LDB(B1, 0, 1); PG8_SCHED; PG8_LDA(At, 0, 0); PG8_STAGE(PG8_SA(1, 1), a1 + hstep, voffA);
;             PG8_WAIT_V(8); PG8_WAIT_L(0); PG8_BAR; PG8_MMA(0, 0, At, B0); PG8_MMA(0, 1, At, B1); PG8_BAR; PG8_SCHED;
;             PG8_LDA(At, 0, 1); PG8_STAGE(PG8_SB(0, 0), b2, voffB); PG8_STAGE(PG8_SB(0, 1), b2 + hstep, voffB); PG8_STAGE(PG8_SA(0, 0), a2, voffA);
;             PG8_WAIT_V(8); PG8_WAIT_L(0); PG8_BAR; PG8_MMA(1, 0, At, B0); PG8_MMA(1, 1, At, B1); PG8_BAR; PG8_SCHED;
.LBB0_798:
	s_add_u32 s68, s66, 0x100
	s_addc_u32 s69, s67, 0
	s_add_i32 s56, 0, 0x10000
	s_cmp_eq_u32 s23, 40
	s_cselect_b32 s73, s9, s69
	s_cselect_b32 s72, s8, s68
	s_cselect_b32 s71, s65, s22
	s_cselect_b32 s70, s64, s51
	s_add_i32 s58, 0, 0x14000
	v_add_u32_e32 v92, s56, v175
	v_add_u32_e32 v158, s58, v175
	ds_read_b128 v[72:75], v92
	ds_read_b128 v[76:79], v92 offset:1024
	ds_read_b128 v[88:91], v92 offset:2048
	ds_read_b128 v[92:95], v92 offset:3072
	ds_read_b128 v[150:153], v158
	ds_read_b128 v[154:157], v158 offset:1024
	ds_read_b128 v[162:165], v158 offset:2048
	ds_read_b128 v[166:169], v158 offset:3072
	v_lshl_add_u64 v[158:159], s[66:67], 0, v[146:147]
	s_add_i32 m0, s35, 0xc000
	ds_read_b128 v[170:173], v179
	ds_read_b128 v[180:183], v179 offset:1024
	ds_read_b128 v[184:187], v179 offset:2048
	ds_read_b128 v[188:191], v179 offset:3072
	ds_read_b128 v[192:195], v179 offset:4096
	ds_read_b128 v[196:199], v179 offset:5120
	ds_read_b128 v[200:203], v179 offset:6144
	ds_read_b128 v[204:207], v179 offset:7168
	global_load_lds_dwordx4 v[158:159], off
	v_lshl_add_u64 v[158:159], s[66:67], 0, v[148:149]
	s_add_i32 m0, s35, 0xe000
	s_nop 0
	global_load_lds_dwordx4 v[158:159], off
	s_waitcnt vmcnt(8)
	s_waitcnt lgkmcnt(0)
	s_barrier
	s_setprio 1
	v_mfma_f32_16x16x32_bf16 v[140:143], v[72:75], v[170:173], v[140:143]
	v_mfma_f32_16x16x32_bf16 v[136:139], v[88:91], v[170:173], v[136:139]
	v_mfma_f32_16x16x32_bf16 v[124:127], v[72:75], v[184:187], v[124:127]
	v_mfma_f32_16x16x32_bf16 v[120:123], v[88:91], v[184:187], v[120:123]
	v_mfma_f32_16x16x32_bf16 v[108:111], v[72:75], v[192:195], v[108:111]
	v_mfma_f32_16x16x32_bf16 v[104:107], v[88:91], v[192:195], v[104:107]
	v_mfma_f32_16x16x32_bf16 v[84:87], v[72:75], v[200:203], v[84:87]
	v_mfma_f32_16x16x32_bf16 v[80:83], v[88:91], v[200:203], v[80:83]
	v_mfma_f32_16x16x32_bf16 v[140:143], v[76:79], v[180:183], v[140:143]
	v_mfma_f32_16x16x32_bf16 v[136:139], v[92:95], v[180:183], v[136:139]
	v_mfma_f32_16x16x32_bf16 v[124:127], v[76:79], v[188:191], v[124:127]
	v_mfma_f32_16x16x32_bf16 v[120:123], v[92:95], v[188:191], v[120:123]
	v_mfma_f32_16x16x32_bf16 v[108:111], v[76:79], v[196:199], v[108:111]
	v_mfma_f32_16x16x32_bf16 v[104:107], v[92:95], v[196:199], v[104:107]
	v_mfma_f32_16x16x32_bf16 v[84:87], v[76:79], v[204:207], v[84:87]
	v_mfma_f32_16x16x32_bf16 v[80:83], v[92:95], v[204:207], v[80:83]
	s_setprio 0
	s_setprio 1
	v_mfma_f32_16x16x32_bf16 v[132:135], v[150:153], v[170:173], v[132:135]
	v_mfma_f32_16x16x32_bf16 v[128:131], v[162:165], v[170:173], v[128:131]
	v_mfma_f32_16x16x32_bf16 v[116:119], v[150:153], v[184:187], v[116:119]
	v_mfma_f32_16x16x32_bf16 v[112:115], v[162:165], v[184:187], v[112:115]
	v_mfma_f32_16x16x32_bf16 v[100:103], v[150:153], v[192:195], v[100:103]
	v_mfma_f32_16x16x32_bf16 v[96:99], v[162:165], v[192:195], v[96:99]
	v_mfma_f32_16x16x32_bf16 v[68:71], v[150:153], v[200:203], v[68:71]
	v_mfma_f32_16x16x32_bf16 v[64:67], v[162:165], v[200:203], v[64:67]
	v_mfma_f32_16x16x32_bf16 v[132:135], v[154:157], v[180:183], v[132:135]
	v_mfma_f32_16x16x32_bf16 v[128:131], v[166:169], v[180:183], v[128:131]
	v_mfma_f32_16x16x32_bf16 v[116:119], v[154:157], v[188:191], v[116:119]
	v_mfma_f32_16x16x32_bf16 v[112:115], v[166:169], v[188:191], v[112:115]
	v_mfma_f32_16x16x32_bf16 v[100:103], v[154:157], v[196:199], v[100:103]
	v_mfma_f32_16x16x32_bf16 v[96:99], v[166:169], v[196:199], v[96:99]
	v_mfma_f32_16x16x32_bf16 v[68:71], v[154:157], v[204:207], v[68:71]
	v_mfma_f32_16x16x32_bf16 v[64:67], v[166:169], v[204:207], v[64:67]
	s_setprio 0
	s_barrier
	s_add_i32 s56, s56, s3
	v_lshl_add_u64 v[158:159], s[70:71], 0, v[160:161]
	s_mov_b32 m0, s56
	ds_read_b128 v[170:173], v179 offset:16384
	ds_read_b128 v[180:183], v179 offset:17408
	ds_read_b128 v[184:187], v179 offset:18432
	ds_read_b128 v[188:191], v179 offset:19456
	ds_read_b128 v[192:195], v179 offset:20480
	ds_read_b128 v[196:199], v179 offset:21504
	ds_read_b128 v[200:203], v179 offset:22528
	ds_read_b128 v[204:207], v179 offset:23552
	global_load_lds_dwordx4 v[158:159], off
	s_add_i32 m0, s56, 0x2000
	s_add_u32 s56, s70, 0xb0000
	v_lshl_add_u64 v[208:209], s[70:71], 0, v[144:145]
	s_addc_u32 s57, s71, 0
	s_add_i32 s58, s58, s3
	global_load_lds_dwordx4 v[208:209], off
	v_lshl_add_u64 v[210:211], s[56:57], 0, v[160:161]
	s_mov_b32 m0, s58
	v_lshl_add_u64 v[212:213], s[72:73], 0, v[144:145]
	global_load_lds_dwordx4 v[210:211], off
	v_lshl_add_u64 v[210:211], s[56:57], 0, v[144:145]
	s_add_i32 m0, s58, 0x2000
	s_nop 0
	global_load_lds_dwordx4 v[210:211], off
	v_lshl_add_u64 v[210:211], s[72:73], 0, v[160:161]
	s_mov_b32 m0, s35
	s_nop 0
	global_load_lds_dwordx4 v[210:211], off
	s_mov_b32 m0, s76
	s_nop 0
	global_load_lds_dwordx4 v[212:213], off
	s_waitcnt vmcnt(8)
	s_waitcnt lgkmcnt(0)
	s_barrier
; #define PG8_STAGE(bufoff, gbase, voff) do { _Pragma("unroll") for (int _i = 0; _i < 2; ++_i) \
;         __builtin_amdgcn_global_load_lds((const unsigned*)((const char*)(gbase) + (voff)[_i]), (PG8_LAS unsigned*)(lds + (bufoff) + ldsw + _i * 8192), 16, 0, 0); } while (0)
; #define PG8_LDA(dst, b, h) do { _Pragma("unroll") for (int m = 0; m < 4; ++m) _Pragma("unroll") for (int k = 0; k < 2; ++k) dst[m][k] = *(const PG8_LAS bf16x8*)(lds + PG8_SA(b, h) + aoff + m * 2048 + k * 1024); } while (0)
; #define PG8_LDB(dst, b, h) do { _Pragma("unroll") for (int n = 0; n < 2; ++n) _Pragma("unroll") for (int k = 0; k < 2; ++k) dst[n][k] = *(const PG8_LAS bf16x8*)(lds + PG8_SB(b, h) + boff + n * 2048 + k * 1024); } while (0)
; #define PG8_MMA(ai, bj, At, Bt) do { __builtin_amdgcn_s_setprio(1); _Pragma("unroll") for (int m = 0; m < 4; ++m) _Pragma("unroll") for (int n = 0; n < 2; ++n) _Pragma("unroll") for (int k = 0; k < 2; ++k) \
;         acc[ai][bj][m][n] = __builtin_amdgcn_mfma_f32_16x16x32_bf16(Bt[n][k], At[m][k], acc[ai][bj][m][n], 0, 0, 0); __builtin_amdgcn_s_setprio(0); } while (0)
; #define PG8_WAIT_V(n) asm volatile("s_waitcnt vmcnt(" #n ")" ::: "memory")
; #define PG8_WAIT_L(n) asm volatile("s_waitcnt lgkmcnt(" #n ")" ::: "memory")
; #define PG8_BAR __builtin_amdgcn_s_barrier()
; #define PG8_SCHED __builtin_amdgcn_sched_barrier(0)
; template <class Epi, class Sched, bool ALIGN_EPI = false, bool SP2 = false>
; __device__ __forceinline__ void gemm_phase(PG8_LAS unsigned char* lds, const Gemm g, const Sched& S, const Epi& E) {
;     ...
;             PG8_WAIT_V(8); PG8_WAIT_L(0); PG8_BAR; PG8_MMA(1, 0, At, B0); PG8_MMA(1, 1, At, B1); PG8_BAR; PG8_SCHED;
;             PG8_LDB(B0, 1, 0); PG8_LDB(B1, 1, 1); PG8_SCHED; PG8_LDA(At, 1, 0); PG8_STAGE(PG8_SA(0, 1), a2 + hstep, voffA);
;             PG8_WAIT_V(8); PG8_WAIT_L(0); PG8_BAR; PG8_MMA(0, 0, At, B0); PG8_MMA(0, 1, At, B1); PG8_BAR; PG8_SCHED;
	s_setprio 1
	v_mfma_f32_16x16x32_bf16 v[60:63], v[72:75], v[170:173], v[60:63]
	v_mfma_f32_16x16x32_bf16 v[56:59], v[88:91], v[170:173], v[56:59]
	v_mfma_f32_16x16x32_bf16 v[44:47], v[72:75], v[184:187], v[44:47]
	v_mfma_f32_16x16x32_bf16 v[40:43], v[88:91], v[184:187], v[40:43]
	v_mfma_f32_16x16x32_bf16 v[28:31], v[72:75], v[192:195], v[28:31]
	v_mfma_f32_16x16x32_bf16 v[24:27], v[88:91], v[192:195], v[24:27]
	v_mfma_f32_16x16x32_bf16 v[12:15], v[72:75], v[200:203], v[12:15]
	v_mfma_f32_16x16x32_bf16 v[8:11], v[88:91], v[200:203], v[8:11]
	v_mfma_f32_16x16x32_bf16 v[60:63], v[76:79], v[180:183], v[60:63]
	v_mfma_f32_16x16x32_bf16 v[56:59], v[92:95], v[180:183], v[56:59]
	v_mfma_f32_16x16x32_bf16 v[44:47], v[76:79], v[188:191], v[44:47]
	v_mfma_f32_16x16x32_bf16 v[40:43], v[92:95], v[188:191], v[40:43]
	v_mfma_f32_16x16x32_bf16 v[28:31], v[76:79], v[196:199], v[28:31]
	v_mfma_f32_16x16x32_bf16 v[24:27], v[92:95], v[196:199], v[24:27]
	v_mfma_f32_16x16x32_bf16 v[12:15], v[76:79], v[204:207], v[12:15]
	v_mfma_f32_16x16x32_bf16 v[8:11], v[92:95], v[204:207], v[8:11]
	s_setprio 0
	s_setprio 1
	v_mfma_f32_16x16x32_bf16 v[52:55], v[150:153], v[170:173], v[52:55]
	v_mfma_f32_16x16x32_bf16 v[48:51], v[162:165], v[170:173], v[48:51]
	v_mfma_f32_16x16x32_bf16 v[36:39], v[150:153], v[184:187], v[36:39]
	v_mfma_f32_16x16x32_bf16 v[32:35], v[162:165], v[184:187], v[32:35]
	v_mfma_f32_16x16x32_bf16 v[20:23], v[150:153], v[192:195], v[20:23]
	v_mfma_f32_16x16x32_bf16 v[16:19], v[162:165], v[192:195], v[16:19]
	v_mfma_f32_16x16x32_bf16 v[4:7], v[150:153], v[200:203], v[4:7]
	v_mfma_f32_16x16x32_bf16 v[0:3], v[162:165], v[200:203], v[0:3]
	v_mfma_f32_16x16x32_bf16 v[52:55], v[154:157], v[180:183], v[52:55]
	v_mfma_f32_16x16x32_bf16 v[48:51], v[166:169], v[180:183], v[48:51]
	v_mfma_f32_16x16x32_bf16 v[36:39], v[154:157], v[188:191], v[36:39]
	v_mfma_f32_16x16x32_bf16 v[32:35], v[166:169], v[188:191], v[32:35]
	v_mfma_f32_16x16x32_bf16 v[20:23], v[154:157], v[196:199], v[20:23]
	v_mfma_f32_16x16x32_bf16 v[16:19], v[166:169], v[196:199], v[16:19]
	v_mfma_f32_16x16x32_bf16 v[4:7], v[154:157], v[204:207], v[4:7]
	v_mfma_f32_16x16x32_bf16 v[0:3], v[166:169], v[204:207], v[0:3]
	s_setprio 0
	s_barrier
	s_add_i32 s58, 0, 0x18000
	s_add_i32 s59, 0, 0x1c000
	v_add_u32_e32 v92, s58, v175
	v_add_u32_e32 v166, s59, v175
	ds_read_b128 v[72:75], v92
	ds_read_b128 v[76:79], v92 offset:1024
	ds_read_b128 v[88:91], v92 offset:2048
	ds_read_b128 v[92:95], v92 offset:3072
	ds_read_b128 v[150:153], v166
	ds_read_b128 v[154:157], v166 offset:1024
	ds_read_b128 v[162:165], v166 offset:2048
	ds_read_b128 v[166:169], v166 offset:3072
	s_add_u32 s56, s72, 0xb0000
	s_addc_u32 s57, s73, 0
	s_mov_b32 m0, s77
	v_lshl_add_u64 v[214:215], s[56:57], 0, v[160:161]
	ds_read_b128 v[170:173], v179 offset:32768
	ds_read_b128 v[180:183], v179 offset:33792
	ds_read_b128 v[184:187], v179 offset:34816
	ds_read_b128 v[188:191], v179 offset:35840
	ds_read_b128 v[192:195], v179 offset:36864
	ds_read_b128 v[196:199], v179 offset:37888
	ds_read_b128 v[200:203], v179 offset:38912
	ds_read_b128 v[204:207], v179 offset:39936
	global_load_lds_dwordx4 v[214:215], off
	v_lshl_add_u64 v[214:215], s[56:57], 0, v[144:145]
	s_mov_b32 m0, s78
	s_nop 0
	global_load_lds_dwordx4 v[214:215], off
	s_waitcnt vmcnt(8)
	s_waitcnt lgkmcnt(0)
	s_barrier
	s_setprio 1
	v_mfma_f32_16x16x32_bf16 v[140:143], v[72:75], v[170:173], v[140:143]
	v_mfma_f32_16x16x32_bf16 v[136:139], v[88:91], v[170:173], v[136:139]
	v_mfma_f32_16x16x32_bf16 v[124:127], v[72:75], v[184:187], v[124:127]
	v_mfma_f32_16x16x32_bf16 v[120:123], v[88:91], v[184:187], v[120:123]
	v_mfma_f32_16x16x32_bf16 v[108:111], v[72:75], v[192:195], v[108:111]
	v_mfma_f32_16x16x32_bf16 v[104:107], v[88:91], v[192:195], v[104:107]
	v_mfma_f32_16x16x32_bf16 v[84:87], v[72:75], v[200:203], v[84:87]
	v_mfma_f32_16x16x32_bf16 v[80:83], v[88:91], v[200:203], v[80:83]
	v_mfma_f32_16x16x32_bf16 v[140:143], v[76:79], v[180:183], v[140:143]
	v_mfma_f32_16x16x32_bf16 v[136:139], v[92:95], v[180:183], v[136:139]
	v_mfma_f32_16x16x32_bf16 v[124:127], v[76:79], v[188:191], v[124:127]
	v_mfma_f32_16x16x32_bf16 v[120:123], v[92:95], v[188:191], v[120:123]
	v_mfma_f32_16x16x32_bf16 v[108:111], v[76:79], v[196:199], v[108:111]
	v_mfma_f32_16x16x32_bf16 v[104:107], v[92:95], v[196:199], v[104:107]
	v_mfma_f32_16x16x32_bf16 v[84:87], v[76:79], v[204:207], v[84:87]
	v_mfma_f32_16x16x32_bf16 v[80:83], v[92:95], v[204:207], v[80:83]
	s_setprio 0
	s_setprio 1
	v_mfma_f32_16x16x32_bf16 v[132:135], v[150:153], v[170:173], v[132:135]
	v_mfma_f32_16x16x32_bf16 v[128:131], v[162:165], v[170:173], v[128:131]
	v_mfma_f32_16x16x32_bf16 v[116:119], v[150:153], v[184:187], v[116:119]
	v_mfma_f32_16x16x32_bf16 v[112:115], v[162:165], v[184:187], v[112:115]
	v_mfma_f32_16x16x32_bf16 v[100:103], v[150:153], v[192:195], v[100:103]
	v_mfma_f32_16x16x32_bf16 v[96:99], v[162:165], v[192:195], v[96:99]
	v_mfma_f32_16x16x32_bf16 v[68:71], v[150:153], v[200:203], v[68:71]
	v_mfma_f32_16x16x32_bf16 v[64:67], v[162:165], v[200:203], v[64:67]
	v_mfma_f32_16x16x32_bf16 v[132:135], v[154:157], v[180:183], v[132:135]
	v_mfma_f32_16x16x32_bf16 v[128:131], v[166:169], v[180:183], v[128:131]
	v_mfma_f32_16x16x32_bf16 v[116:119], v[154:157], v[188:191], v[116:119]
	v_mfma_f32_16x16x32_bf16 v[112:115], v[166:169], v[188:191], v[112:115]
	v_mfma_f32_16x16x32_bf16 v[100:103], v[154:157], v[196:199], v[100:103]
	v_mfma_f32_16x16x32_bf16 v[96:99], v[166:169], v[196:199], v[96:99]
	v_mfma_f32_16x16x32_bf16 v[68:71], v[154:157], v[204:207], v[68:71]
	v_mfma_f32_16x16x32_bf16 v[64:67], v[166:169], v[204:207], v[64:67]
	s_setprio 0
	s_barrier
; #define PG8_STAGE(bufoff, gbase, voff) do { _Pragma("unroll") for (int _i = 0; _i < 2; ++_i) \
;         __builtin_amdgcn_global_load_lds((const unsigned*)((const char*)(gbase) + (voff)[_i]), (PG8_LAS unsigned*)(lds + (bufoff) + ldsw + _i * 8192), 16, 0, 0); } while (0)
; #define PG8_LDA(dst, b, h) do { _Pragma("unroll") for (int m = 0; m < 4; ++m) _Pragma("unroll") for (int k = 0; k < 2; ++k) dst[m][k] = *(const PG8_LAS bf16x8*)(lds + PG8_SA(b, h) + aoff + m * 2048 + k * 1024); } while (0)
; #define PG8_MMA(ai, bj, At, Bt) do { __builtin_amdgcn_s_setprio(1); _Pragma("unroll") for (int m = 0; m < 4; ++m) _Pragma("unroll") for (int n = 0; n < 2; ++n) _Pragma("unroll") for (int k = 0; k < 2; ++k) \
;         acc[ai][bj][m][n] = __builtin_amdgcn_mfma_f32_16x16x32_bf16(Bt[n][k], At[m][k], acc[ai][bj][m][n], 0, 0, 0); __builtin_amdgcn_s_setprio(0); } while (0)
; #define PG8_WAIT_V(n) asm volatile("s_waitcnt vmcnt(" #n ")" ::: "memory")
; #define PG8_WAIT_L(n) asm volatile("s_waitcnt lgkmcnt(" #n ")" ::: "memory")
; #define PG8_BAR __builtin_amdgcn_s_barrier()
; #define PG8_SCHED __builtin_amdgcn_sched_barrier(0)
; template <class Epi, class Sched, bool ALIGN_EPI = false, bool SP2 = false>
; __device__ __forceinline__ void gemm_phase(PG8_LAS unsigned char* lds, const Gemm g, const Sched& S, const Epi& E) {
;     ...
;             PG8_LDA(At, 1, 1); PG8_STAGE(PG8_SB(1, 0), b3, voffB); PG8_STAGE(PG8_SB(1, 1), b3 + hstep, voffB); PG8_STAGE(PG8_SA(1, 0), a3, voffA);
;             PG8_WAIT_V(8); PG8_WAIT_L(0); PG8_BAR; PG8_MMA(1, 0, At, B0); PG8_MMA(1, 1, At, B1); PG8_BAR; PG8_SCHED;
	s_add_i32 s56, s58, s3
	v_lshl_add_u64 v[158:159], v[158:159], 0, s[24:25]
	s_mov_b32 m0, s56
	ds_read_b128 v[170:173], v179 offset:49152
	ds_read_b128 v[180:183], v179 offset:50176
	ds_read_b128 v[184:187], v179 offset:51200
	ds_read_b128 v[188:191], v179 offset:52224
	ds_read_b128 v[192:195], v179 offset:53248
	ds_read_b128 v[196:199], v179 offset:54272
	ds_read_b128 v[200:203], v179 offset:55296
	ds_read_b128 v[204:207], v179 offset:56320
	global_load_lds_dwordx4 v[158:159], off
	s_add_i32 m0, s56, 0x2000
	s_add_u32 s56, s70, 0xb0080
	v_lshl_add_u64 v[158:159], v[208:209], 0, s[24:25]
	s_addc_u32 s57, s71, 0
	s_add_i32 s58, s59, s3
	global_load_lds_dwordx4 v[158:159], off
	v_lshl_add_u64 v[158:159], s[56:57], 0, v[160:161]
	s_mov_b32 m0, s58
	s_nop 0
	global_load_lds_dwordx4 v[158:159], off
	v_lshl_add_u64 v[158:159], s[56:57], 0, v[144:145]
	s_add_i32 m0, s58, 0x2000
	s_nop 0
	global_load_lds_dwordx4 v[158:159], off
	v_lshl_add_u64 v[158:159], v[210:211], 0, s[24:25]
	s_mov_b32 m0, s81
	s_nop 0
	global_load_lds_dwordx4 v[158:159], off
	v_lshl_add_u64 v[158:159], v[212:213], 0, s[24:25]
	s_mov_b32 m0, s82
	s_nop 0
	global_load_lds_dwordx4 v[158:159], off
	s_waitcnt vmcnt(8)
	s_waitcnt lgkmcnt(0)
	s_barrier
	s_setprio 1
	v_mfma_f32_16x16x32_bf16 v[60:63], v[72:75], v[170:173], v[60:63]
	v_mfma_f32_16x16x32_bf16 v[56:59], v[88:91], v[170:173], v[56:59]
	v_mfma_f32_16x16x32_bf16 v[44:47], v[72:75], v[184:187], v[44:47]
	v_mfma_f32_16x16x32_bf16 v[40:43], v[88:91], v[184:187], v[40:43]
	v_mfma_f32_16x16x32_bf16 v[28:31], v[72:75], v[192:195], v[28:31]
	v_mfma_f32_16x16x32_bf16 v[24:27], v[88:91], v[192:195], v[24:27]
	v_mfma_f32_16x16x32_bf16 v[12:15], v[72:75], v[200:203], v[12:15]
	v_mfma_f32_16x16x32_bf16 v[8:11], v[88:91], v[200:203], v[8:11]
	v_mfma_f32_16x16x32_bf16 v[60:63], v[76:79], v[180:183], v[60:63]
	v_mfma_f32_16x16x32_bf16 v[56:59], v[92:95], v[180:183], v[56:59]
	v_mfma_f32_16x16x32_bf16 v[44:47], v[76:79], v[188:191], v[44:47]
	v_mfma_f32_16x16x32_bf16 v[40:43], v[92:95], v[188:191], v[40:43]
	v_mfma_f32_16x16x32_bf16 v[28:31], v[76:79], v[196:199], v[28:31]
	v_mfma_f32_16x16x32_bf16 v[24:27], v[92:95], v[196:199], v[24:27]
	v_mfma_f32_16x16x32_bf16 v[12:15], v[76:79], v[204:207], v[12:15]
	v_mfma_f32_16x16x32_bf16 v[8:11], v[92:95], v[204:207], v[8:11]
	s_setprio 0
	s_setprio 1
	v_mfma_f32_16x16x32_bf16 v[52:55], v[150:153], v[170:173], v[52:55]
	v_mfma_f32_16x16x32_bf16 v[48:51], v[162:165], v[170:173], v[48:51]
	v_mfma_f32_16x16x32_bf16 v[36:39], v[150:153], v[184:187], v[36:39]
	v_mfma_f32_16x16x32_bf16 v[32:35], v[162:165], v[184:187], v[32:35]
	v_mfma_f32_16x16x32_bf16 v[20:23], v[150:153], v[192:195], v[20:23]
	v_mfma_f32_16x16x32_bf16 v[16:19], v[162:165], v[192:195], v[16:19]
	v_mfma_f32_16x16x32_bf16 v[4:7], v[150:153], v[200:203], v[4:7]
	v_mfma_f32_16x16x32_bf16 v[0:3], v[162:165], v[200:203], v[0:3]
	v_mfma_f32_16x16x32_bf16 v[52:55], v[154:157], v[180:183], v[52:55]
	v_mfma_f32_16x16x32_bf16 v[48:51], v[166:169], v[180:183], v[48:51]
	v_mfma_f32_16x16x32_bf16 v[36:39], v[154:157], v[188:191], v[36:39]
	v_mfma_f32_16x16x32_bf16 v[32:35], v[166:169], v[188:191], v[32:35]
	v_mfma_f32_16x16x32_bf16 v[20:23], v[154:157], v[196:199], v[20:23]
	v_mfma_f32_16x16x32_bf16 v[16:19], v[166:169], v[196:199], v[16:19]
	v_mfma_f32_16x16x32_bf16 v[4:7], v[154:157], v[204:207], v[4:7]
	v_mfma_f32_16x16x32_bf16 v[0:3], v[166:169], v[204:207], v[0:3]
	s_setprio 0
	s_barrier
	s_add_i32 s23, s23, 2
	s_add_u32 s51, s51, 0x100
	s_addc_u32 s22, s22, 0
	s_cmp_gt_u32 s23, 41
	s_mov_b64 s[66:67], s[68:69]
	s_cbranch_scc0 .LBB0_798
	s_and_b64 vcc, exec, s[12:13]
	s_cbranch_vccz .LBB0_801
	s_barrier
